# nt hint on the mix phase's once-read inputs (attention Q rows, FFT item inputs)
# baseline (speedup 1.0000x reference)
.LBB0_181:
	v_mov_b32_e32 v20, v224
	s_ashr_i32 s0, s31, 1
	s_lshl_b32 s2, s31, 7
	v_readfirstlane_b32 s58, v20
	s_bfe_u32 s59, s58, 0x20006
	s_lshl_b32 s1, s0, 8
	s_and_b32 s2, s2, 0x80
	s_or_b32 s1, s1, s2
	s_lshl_b32 s2, s59, 5
	s_or_b32 s1, s1, s2
	v_and_b32_e32 v21, 31, v20
	s_addk_i32 s1, 0x2000
	s_ashr_i32 s64, s58, 8
	v_or_b32_e32 v192, s1, v21
	v_lshlrev_b64 v[0:1], 11, v[192:193]
	s_lshl_b32 s2, s64, 6
	v_bfe_u32 v163, v20, 5, 1
	v_lshl_add_u64 v[0:1], s[34:35], 0, v[0:1]
	s_ashr_i32 s3, s2, 31
	v_lshl_add_u64 v[0:1], s[2:3], 1, v[0:1]
	v_lshlrev_b32_e32 v160, 4, v163
	v_mov_b32_e32 v161, v193
	v_lshl_add_u64 v[0:1], v[0:1], 0, v[160:161]
	global_load_dwordx4 v[112:115], v[0:1], off nt
	global_load_dwordx4 v[116:119], v[0:1], off offset:32 nt
	global_load_dwordx4 v[120:123], v[0:1], off offset:64 nt
	s_lshl_b32 s1, s0, 3
	global_load_dwordx4 v[124:127], v[0:1], off offset:96 nt
	s_or_b32 s1, s1, s54
	s_lshl_b32 s2, s1, 1
	s_mul_i32 s4, s1, 0x90000
	s_mul_hi_i32 s3, s2, 0x48000
	s_add_u32 s2, s56, s4
	s_addc_u32 s3, s57, s3
	s_mul_hi_i32 s1, s1, 0x90000
	s_add_u32 s48, s44, s4
	s_addc_u32 s49, s45, s1
	s_add_u32 s62, s2, 0x48000
	s_addc_u32 s63, s3, 0
	s_add_u32 s4, s48, 0x48000
	s_addc_u32 s5, s49, 0
	s_lshl_b32 s0, s0, 4
	s_add_i32 s0, s0, s75
	s_add_i32 s0, s0, s64
	s_ashr_i32 s1, s0, 31
	v_ashrrev_i32_e32 v2, 3, v20
	v_and_b32_e32 v3, 7, v20
	s_lshl_b64 s[0:1], s[0:1], 2
	v_readlane_b32 s9, v252, 46
	v_lshlrev_b32_e32 v164, 7, v2
	v_lshlrev_b32_e32 v3, 4, v3
	s_add_u32 s0, s9, s0
	v_readlane_b32 s9, v252, 47
	v_or_b32_e32 v26, v164, v3
	s_addc_u32 s1, s9, s1
	global_load_dwordx4 v[128:131], v26, s[2:3]
	global_load_dwordx4 v[132:135], v26, s[62:63]
	global_load_dword v27, v193, s[0:1]
	v_mul_lo_u32 v2, v2, s7
	v_or_b32_e32 v166, v2, v3
	v_lshrrev_b32_e32 v22, 4, v20
	v_and_b32_e32 v24, 6, v20
	v_bfe_u32 v23, v20, 4, 3
	v_bitop3_b32 v25, v22, v20, 7 bitop3:0x28
	v_lshl_or_b32 v169, v25, 4, v164
	v_lshlrev_b32_e32 v21, 7, v21
	v_mov_b32_e32 v167, 0
	v_mov_b32_e32 v148, 0
	v_and_b32_e32 v165, 63, v20
	s_mov_b32 s71, 0
	v_add_u32_e32 v173, 0, v21
	v_add_u32_e32 v177, 0x4000, v26
	s_mov_b32 s31, 0
	v_mov_b32_e32 v149, v148
	v_mov_b32_e32 v150, v148
	v_mov_b32_e32 v151, v148
	v_mov_b32_e32 v144, v148
	v_mov_b32_e32 v145, v148
	v_mov_b32_e32 v146, v148
	v_mov_b32_e32 v147, v148
	v_mov_b32_e32 v140, v148
	v_mov_b32_e32 v141, v148
	v_mov_b32_e32 v142, v148
	v_mov_b32_e32 v143, v148
	v_mov_b32_e32 v136, v148
	v_mov_b32_e32 v137, v148
	v_mov_b32_e32 v138, v148
	v_mov_b32_e32 v139, v148
	v_mov_b32_e32 v48, 0
	v_mov_b32_e32 v49, v167
	v_mov_b32_e32 v50, v167
	v_mov_b32_e32 v51, v167
	v_mov_b32_e32 v52, v167
	v_mov_b32_e32 v53, v167
	v_mov_b32_e32 v54, v167
	v_mov_b32_e32 v55, v167
	v_mov_b32_e32 v56, v167
	v_mov_b32_e32 v57, v167
	v_mov_b32_e32 v58, v167
	v_mov_b32_e32 v59, v167
	v_mov_b32_e32 v60, v167
	v_mov_b32_e32 v61, v167
	v_mov_b32_e32 v62, v167
	v_mov_b32_e32 v63, v167
	s_waitcnt vmcnt(6)
	v_and_b32_e32 v1, 0xffff0000, v112
	v_and_b32_e32 v3, 0xffff0000, v113
	v_lshlrev_b32_e32 v0, 16, v112
	v_lshlrev_b32_e32 v2, 16, v113
	v_and_b32_e32 v5, 0xffff0000, v114
	v_mul_f32_e32 v1, v1, v1
	v_mul_f32_e32 v3, v3, v3
	v_lshlrev_b32_e32 v4, 16, v114
	v_and_b32_e32 v7, 0xffff0000, v115
	v_mul_f32_e32 v5, v5, v5
	v_fmac_f32_e32 v1, v0, v0
	v_fmac_f32_e32 v3, v2, v2
	v_lshlrev_b32_e32 v6, 16, v115
	s_waitcnt vmcnt(5)
	v_and_b32_e32 v9, 0xffff0000, v116
	v_mul_f32_e32 v7, v7, v7
	v_fmac_f32_e32 v5, v4, v4
	v_add_f32_e32 v0, v1, v3
	v_lshlrev_b32_e32 v8, 16, v116
	v_and_b32_e32 v11, 0xffff0000, v117
	v_mul_f32_e32 v9, v9, v9
	v_fmac_f32_e32 v7, v6, v6
	v_add_f32_e32 v0, v5, v0
	v_lshlrev_b32_e32 v10, 16, v117
	v_and_b32_e32 v13, 0xffff0000, v118
	v_mul_f32_e32 v11, v11, v11
	v_fmac_f32_e32 v9, v8, v8
	v_add_f32_e32 v0, v7, v0
	v_lshlrev_b32_e32 v12, 16, v118
	v_and_b32_e32 v15, 0xffff0000, v119
	v_mul_f32_e32 v13, v13, v13
	v_fmac_f32_e32 v11, v10, v10
	v_add_f32_e32 v0, v9, v0
	v_lshlrev_b32_e32 v14, 16, v119
	v_mul_f32_e32 v15, v15, v15
	v_fmac_f32_e32 v13, v12, v12
	v_add_f32_e32 v0, v11, v0
	v_fmac_f32_e32 v15, v14, v14
	v_add_f32_e32 v0, v13, v0
	v_add_f32_e32 v16, v15, v0
	global_load_dwordx4 v[0:3], v166, s[48:49]
	v_add_u32_e32 v12, 0x2000, v26
	global_load_dwordx4 v[4:7], v166, s[4:5]
	global_load_dwordx4 v[8:11], v12, s[2:3]
	s_nop 0
	global_load_dwordx4 v[12:15], v12, s[62:63]
	s_waitcnt vmcnt(8)
	v_and_b32_e32 v18, 0xffff0000, v120
	v_lshlrev_b32_e32 v17, 16, v120
	v_mul_f32_e32 v18, v18, v18
	v_fmac_f32_e32 v18, v17, v17
	v_add_f32_e32 v16, v18, v16
	v_and_b32_e32 v18, 0xffff0000, v121
	v_lshlrev_b32_e32 v17, 16, v121
	v_mul_f32_e32 v18, v18, v18
	v_fmac_f32_e32 v18, v17, v17
	v_add_f32_e32 v28, v18, v16
	v_and_b32_e32 v19, 0xffff0000, v123
	v_and_b32_e32 v18, 0xffff0000, v122
	v_lshlrev_b32_e32 v17, 16, v123
	v_lshlrev_b32_e32 v16, 16, v122
	v_pk_mul_f32 v[18:19], v[18:19], v[18:19]
	v_mov_b32_e32 v32, 0
	v_pk_fma_f32 v[16:17], v[16:17], v[16:17], v[18:19]
	s_waitcnt vmcnt(7)
	v_and_b32_e32 v19, 0xffff0000, v125
	v_add_f32_e32 v16, v16, v28
	v_and_b32_e32 v18, 0xffff0000, v124
	v_add_f32_e32 v28, v17, v16
	v_lshlrev_b32_e32 v17, 16, v125
	v_lshlrev_b32_e32 v16, 16, v124
	v_pk_mul_f32 v[18:19], v[18:19], v[18:19]
	v_mov_b32_e32 v33, v167
	v_pk_fma_f32 v[16:17], v[16:17], v[16:17], v[18:19]
	v_and_b32_e32 v19, 0xffff0000, v127
	v_add_f32_e32 v16, v16, v28
	v_and_b32_e32 v18, 0xffff0000, v126
	v_add_f32_e32 v28, v17, v16
	v_lshlrev_b32_e32 v17, 16, v127
	v_lshlrev_b32_e32 v16, 16, v126
	v_pk_mul_f32 v[18:19], v[18:19], v[18:19]
	v_mov_b32_e32 v34, v167
	v_pk_fma_f32 v[16:17], v[16:17], v[16:17], v[18:19]
	v_and_b32_e32 v18, 64, v229
	v_add_f32_e32 v16, v16, v28
	v_add_f32_e32 v16, v17, v16
	v_xor_b32_e32 v17, 32, v229
	v_add_u32_e32 v18, 64, v18
	v_cmp_lt_i32_e32 vcc, v17, v18
	v_lshlrev_b32_e32 v19, 3, v20
	v_bitop3_b32 v18, v22, v24, 7 bitop3:0x6c
	v_cndmask_b32_e32 v17, v229, v17, vcc
	v_lshlrev_b32_e32 v161, 2, v17
	ds_bpermute_b32 v17, v161, v16
	v_and_b32_e32 v19, 8, v19
	v_bitop3_b32 v22, v24, v23, 1 bitop3:0x36
	v_lshl_or_b32 v171, v18, 4, v19
	v_lshl_or_b32 v168, v22, 4, v19
	s_waitcnt lgkmcnt(0)
	v_add_f32_e32 v16, v16, v17
	s_waitcnt vmcnt(4)
	v_mul_f32_e32 v16, v27, v16
	v_mul_f32_e32 v17, 0x4f800000, v16
	v_cmp_gt_f32_e32 vcc, s92, v16
	v_mov_b32_e32 v35, v167
	v_mov_b32_e32 v36, v167
	v_cndmask_b32_e32 v16, v16, v17, vcc
	v_sqrt_f32_e32 v17, v16
	v_mov_b32_e32 v37, v167
	v_mov_b32_e32 v38, v167
	v_mov_b32_e32 v39, v167
	v_add_u32_e32 v18, -1, v17
	v_fma_f32 v19, -v18, v17, v16
	v_cmp_ge_f32_e64 s[0:1], 0, v19
	v_add_u32_e32 v19, 1, v17
	v_mov_b32_e32 v40, v167
	v_cndmask_b32_e64 v18, v17, v18, s[0:1]
	v_fma_f32 v17, -v19, v17, v16
	v_cmp_lt_f32_e64 s[0:1], 0, v17
	v_mov_b32_e32 v41, v167
	v_mov_b32_e32 v42, v167
	v_cndmask_b32_e64 v17, v18, v19, s[0:1]
	v_mul_f32_e32 v18, 0x37800000, v17
	v_cndmask_b32_e32 v17, v17, v18, vcc
	v_cmp_class_f32_e32 vcc, v16, v228
	v_add_u32_e32 v18, 0, v164
	v_add_u32_e32 v19, v18, v171
	v_cndmask_b32_e32 v16, v17, v16, vcc
	v_fmamk_f32 v16, v16, 0x3f828f5c, v227
	v_add_u32_e32 v17, 0, v169
	v_xor_b32_e32 v64, 0x80000000, v16
	v_lshrrev_b32_e32 v16, 1, v20
	s_lshl_b32 s0, s64, 13
	ds_write_b128 v17, v[128:131]
	ds_write_b128 v17, v[132:135] offset:8192
	s_waitcnt vmcnt(3)
	ds_write_b64 v19, v[0:1] offset:49152
	v_add_u32_e32 v0, v18, v168
	s_waitcnt vmcnt(2)
	ds_write_b64 v19, v[4:5] offset:57344
	ds_write2st64_b64 v0, v[2:3], v[6:7] offset0:96 offset1:112
	s_waitcnt vmcnt(1)
	ds_write_b128 v17, v[8:11] offset:16384
	s_waitcnt vmcnt(0)
	ds_write_b128 v17, v[12:15] offset:24576
	s_add_i32 s0, s0, 0
	v_bitop3_b32 v0, v163, v16, 7 bitop3:0x78
	v_add_u32_e32 v176, s0, v21
	v_lshlrev_b32_e32 v175, 4, v0
	v_add_u32_e32 v4, v176, v175
	s_waitcnt lgkmcnt(0)
	s_barrier
	ds_read_b128 v[0:3], v4
	ds_read_b128 v[4:7], v4 offset:4096
	v_mov_b32_e32 v65, v64
	v_mov_b32_e32 v66, v64
	v_mov_b32_e32 v67, v64
	v_mov_b32_e32 v68, v64
	v_mov_b32_e32 v69, v64
	v_mov_b32_e32 v70, v64
	v_mov_b32_e32 v71, v64
	v_mov_b32_e32 v72, v64
	v_mov_b32_e32 v73, v64
	v_mov_b32_e32 v74, v64
	v_mov_b32_e32 v75, v64
	v_mov_b32_e32 v76, v64
	v_mov_b32_e32 v77, v64
	v_mov_b32_e32 v78, v64
	v_mov_b32_e32 v79, v64
	v_bfe_u32 v16, v20, 1, 3
	v_mov_b32_e32 v43, v167
	s_waitcnt lgkmcnt(1)
	v_mfma_f32_32x32x16_bf16 v[96:111], v[0:3], v[112:115], v[64:79]
	v_bitop3_b32 v0, v163, v16, 2 bitop3:0x36
	v_lshlrev_b32_e32 v174, 4, v0
	v_add_u32_e32 v8, v176, v174
	ds_read_b128 v[0:3], v8
	ds_read_b128 v[8:11], v8 offset:4096
	v_mov_b32_e32 v44, v167
	v_mov_b32_e32 v45, v167
	v_mov_b32_e32 v46, v167
	s_waitcnt lgkmcnt(2)
	v_mfma_f32_32x32x16_bf16 v[80:95], v[4:7], v[112:115], v[64:79]
	v_mov_b32_e32 v47, v167
	v_mov_b32_e32 v20, v167
	v_mov_b32_e32 v21, v167
	v_mov_b32_e32 v22, v167
	v_mov_b32_e32 v23, v167
	v_mov_b32_e32 v24, v167
	v_mov_b32_e32 v25, v167
	s_waitcnt lgkmcnt(1)
	v_mfma_f32_32x32x16_bf16 v[96:111], v[0:3], v[116:119], v[96:111]
	v_bitop3_b32 v0, v163, v16, 4 bitop3:0x36
	v_lshlrev_b32_e32 v172, 4, v0
	v_add_u32_e32 v12, v176, v172
	ds_read_b128 v[0:3], v12
	ds_read_b128 v[12:15], v12 offset:4096
	v_mov_b32_e32 v26, v167
	v_mov_b32_e32 v27, v167
	v_mov_b32_e32 v28, v167
	s_waitcnt lgkmcnt(2)
	v_mfma_f32_32x32x16_bf16 v[80:95], v[8:11], v[116:119], v[80:95]
	v_mov_b32_e32 v29, v167
	v_mov_b32_e32 v30, v167
	v_mov_b32_e32 v31, v167
	v_mov_b32_e32 v4, v167
	v_mov_b32_e32 v5, v167
	v_mov_b32_e32 v6, v167
	v_mov_b32_e32 v7, v167
	s_waitcnt lgkmcnt(1)
	v_mfma_f32_32x32x16_bf16 v[96:111], v[0:3], v[120:123], v[96:111]
	v_bitop3_b32 v0, v163, v16, 6 bitop3:0x36
	v_lshlrev_b32_e32 v170, 4, v0
	v_add_u32_e32 v16, v176, v170
	ds_read_b128 v[0:3], v16
	ds_read_b128 v[16:19], v16 offset:4096
	v_mov_b32_e32 v8, v167
	v_mov_b32_e32 v9, v167
	v_mov_b32_e32 v10, v167
	s_waitcnt lgkmcnt(2)
	v_mfma_f32_32x32x16_bf16 v[80:95], v[12:15], v[120:123], v[80:95]
	v_mov_b32_e32 v11, v167
	v_mov_b32_e32 v12, v167
	v_mov_b32_e32 v13, v167
	v_mov_b32_e32 v14, v167
	v_mov_b32_e32 v15, v167
	s_waitcnt lgkmcnt(1)
	v_mfma_f32_32x32x16_bf16 v[96:111], v[0:3], v[124:127], v[96:111]
	v_mov_b32_e32 v0, 0
	v_mov_b32_e32 v1, v167
	v_mov_b32_e32 v2, v167
	v_mov_b32_e32 v3, v167
	s_waitcnt lgkmcnt(0)
	v_mfma_f32_32x32x16_bf16 v[80:95], v[16:19], v[124:127], v[80:95]
	v_mov_b32_e32 v16, 0
	v_mov_b32_e32 v17, v167
	v_mov_b32_e32 v18, v167
	v_mov_b32_e32 v19, v167

.LBB0_203:
	s_andn2_b64 vcc, exec, s[0:1]
	s_cbranch_vccnz .LBB0_205
	s_add_i32 s0, s40, s41
	s_lshr_b32 s1, s0, 7
	s_lshl_b32 s0, s0, 2
	v_mov_b32_e32 v0, v224
	s_and_b32 s0, s0, 0x1fc
	s_lshl_b32 s2, s1, 13
	v_readlane_b32 s4, v252, 48
	v_ashrrev_i32_e32 v24, 8, v0
	v_readlane_b32 s5, v252, 49
	s_add_u32 s2, s4, s2
	v_add_u32_e32 v2, s0, v24
	s_addc_u32 s3, s5, 0
	v_lshlrev_b32_sdwa v192, v231, v0 dst_sel:DWORD dst_unused:UNUSED_PAD src0_sel:DWORD src1_sel:BYTE_0
	v_ashrrev_i32_e32 v3, 31, v2
	v_lshl_add_u64 v[4:5], s[2:3], 0, v[192:193]
	v_lshlrev_b64 v[2:3], 15, v[2:3]
	v_lshl_add_u64 v[2:3], v[4:5], 0, v[2:3]
	global_load_dwordx4 v[8:11], v[2:3], off nt
	v_add_co_u32_e32 v2, vcc, s30, v2
	s_movk_i32 s2, 0x4400
	s_nop 0
	v_addc_co_u32_e32 v3, vcc, 0, v3, vcc
	global_load_dwordx4 v[12:15], v[2:3], off nt
	v_add_u32_e32 v2, 0x200, v0
	v_ashrrev_i32_e32 v25, 8, v2
	v_add_u32_e32 v6, s0, v25
	v_ashrrev_i32_e32 v7, 31, v6
	v_lshlrev_b64 v[6:7], 15, v[6:7]
	v_lshl_add_u64 v[4:5], v[4:5], 0, v[6:7]
	global_load_dwordx4 v[16:19], v[4:5], off nt
	v_add_co_u32_e32 v4, vcc, s30, v4
	v_lshlrev_b32_sdwa v3, v232, v0 dst_sel:DWORD dst_unused:UNUSED_PAD src0_sel:DWORD src1_sel:BYTE_0
	s_nop 0
	v_addc_co_u32_e32 v5, vcc, 0, v5, vcc
	global_load_dwordx4 v[20:23], v[4:5], off nt
	v_bfe_u32 v5, v0, 1, 7
	v_lshlrev_b32_e32 v4, 3, v5
	v_add3_u32 v4, 0, v3, v4
	v_mul_i32_i24_e32 v7, 0x4400, v24
	v_mul_i32_i24_e32 v3, 0x4400, v25
	v_mad_i32_i24 v6, v24, s2, v4
	v_mad_i32_i24 v4, v25, s2, v4
	v_readlane_b32 s4, v254, 16
	v_readlane_b32 s5, v254, 17
	s_mov_b32 s5, s70
	v_lshlrev_b32_sdwa v1, v230, v0 dst_sel:DWORD dst_unused:UNUSED_PAD src0_sel:DWORD src1_sel:BYTE_0
	s_lshl_b32 s1, s1, 23
	s_waitcnt vmcnt(0)
	v_lshlrev_b32_e32 v26, 16, v9
	v_and_b32_e32 v28, 0xffff0000, v9
	v_lshlrev_b32_e32 v32, 16, v11
	v_and_b32_e32 v34, 0xffff0000, v11
	v_lshlrev_b32_e32 v24, 16, v8
	v_and_b32_e32 v8, 0xffff0000, v8
	v_lshlrev_b32_e32 v9, 16, v12
	v_and_b32_e32 v11, 0xffff0000, v12
	v_lshlrev_b32_e32 v27, 16, v13
	v_and_b32_e32 v13, 0xffff0000, v13
	v_lshlrev_b32_e32 v31, 16, v14
	v_and_b32_e32 v33, 0xffff0000, v14
	v_lshlrev_b32_e32 v35, 16, v15
	v_and_b32_e32 v15, 0xffff0000, v15
	v_xor_b32_e32 v25, 0x80000000, v9
	v_xor_b32_e32 v9, 0x80000000, v11
	v_lshlrev_b32_e32 v30, 16, v10
	v_and_b32_e32 v10, 0xffff0000, v10
	v_xor_b32_e32 v27, 0x80000000, v27
	v_xor_b32_e32 v29, 0x80000000, v13
	v_xor_b32_e32 v31, 0x80000000, v31
	v_xor_b32_e32 v11, 0x80000000, v33
	v_xor_b32_e32 v33, 0x80000000, v35
	v_xor_b32_e32 v35, 0x80000000, v15
	ds_write2_b64 v6, v[24:25], v[8:9] offset1:1
	ds_write2_b64 v6, v[26:27], v[28:29] offset0:2 offset1:3
	ds_write2_b64 v6, v[30:31], v[10:11] offset0:4 offset1:5
	ds_write2_b64 v6, v[32:33], v[34:35] offset0:6 offset1:7
	v_lshlrev_b32_e32 v6, 16, v23
	v_lshlrev_b32_e32 v13, 16, v20
	v_and_b32_e32 v15, 0xffff0000, v20
	v_xor_b32_e32 v9, 0x80000000, v6
	v_and_b32_e32 v6, 0xffff0000, v23
	v_lshlrev_b32_e32 v12, 16, v16
	v_and_b32_e32 v14, 0xffff0000, v16
	v_lshlrev_b32_e32 v16, 16, v17
	v_and_b32_e32 v36, 0xffff0000, v17
	v_lshlrev_b32_e32 v38, 16, v18
	v_and_b32_e32 v40, 0xffff0000, v18
	v_lshlrev_b32_e32 v17, 16, v21
	v_and_b32_e32 v18, 0xffff0000, v21
	v_lshlrev_b32_e32 v20, 16, v22
	v_and_b32_e32 v21, 0xffff0000, v22
	v_xor_b32_e32 v13, 0x80000000, v13
	v_xor_b32_e32 v15, 0x80000000, v15
	v_lshlrev_b32_e32 v8, 16, v19
	v_and_b32_e32 v10, 0xffff0000, v19
	v_xor_b32_e32 v11, 0x80000000, v6
	v_xor_b32_e32 v17, 0x80000000, v17
	v_xor_b32_e32 v37, 0x80000000, v18
	v_xor_b32_e32 v39, 0x80000000, v20
	v_xor_b32_e32 v41, 0x80000000, v21
	ds_write2_b64 v4, v[12:13], v[14:15] offset1:1
	ds_write2_b64 v4, v[16:17], v[36:37] offset0:2 offset1:3
	ds_write2_b64 v4, v[38:39], v[40:41] offset0:4 offset1:5
	ds_write2_b64 v4, v[8:9], v[10:11] offset0:6 offset1:7
	v_lshrrev_b32_e32 v4, 7, v0
	v_and_b32_e32 v6, 0x7f, v0
	v_mul_lo_u32 v4, v4, s2
	v_or_b32_e32 v18, 0x200, v6
	v_or_b32_e32 v26, 0x400, v6
	v_or_b32_e32 v34, 0x600, v6
	v_add_u32_e32 v16, 0, v4
	v_lshrrev_b32_e32 v8, 1, v0
	v_lshrrev_b32_e32 v18, 1, v18
	v_lshrrev_b32_e32 v26, 1, v26
	v_lshrrev_b32_e32 v34, 1, v34
	v_lshl_add_u32 v4, v6, 3, v16
	v_and_b32_e32 v8, 56, v8
	v_and_b32_e32 v18, 0x138, v18
	v_and_b32_e32 v26, 0x238, v26
	v_and_b32_e32 v34, 0x338, v34
	v_add_u32_e32 v17, v4, v8
	v_or_b32_e32 v8, 0x80, v6
	v_add_u32_e32 v59, v4, v18
	v_or_b32_e32 v18, 0x280, v6
	v_add_u32_e32 v63, v4, v26
	v_or_b32_e32 v26, 0x480, v6
	v_add_u32_e32 v67, v4, v34
	v_or_b32_e32 v34, 0x680, v6
	v_lshrrev_b32_e32 v8, 1, v8
	v_lshrrev_b32_e32 v18, 1, v18
	v_lshrrev_b32_e32 v26, 1, v26
	v_lshrrev_b32_e32 v34, 1, v34
	v_and_b32_e32 v8, 0x78, v8
	v_and_b32_e32 v18, 0x178, v18
	v_and_b32_e32 v26, 0x278, v26
	v_and_b32_e32 v34, 0x378, v34
	v_add_u32_e32 v56, v4, v8
	v_or_b32_e32 v8, 0x100, v6
	v_add_u32_e32 v60, v4, v18
	v_or_b32_e32 v18, 0x300, v6
	v_add_u32_e32 v64, v4, v26
	v_or_b32_e32 v26, 0x500, v6
	v_add_u32_e32 v68, v4, v34
	v_or_b32_e32 v34, 0x700, v6
	v_lshrrev_b32_e32 v8, 1, v8
	v_lshrrev_b32_e32 v18, 1, v18
	v_lshrrev_b32_e32 v26, 1, v26
	v_lshrrev_b32_e32 v34, 1, v34
	v_and_b32_e32 v8, 0xb8, v8
	v_and_b32_e32 v18, 0x1b8, v18
	v_and_b32_e32 v26, 0x2b8, v26
	v_and_b32_e32 v34, 0x3b8, v34
	v_add_u32_e32 v57, v4, v8
	v_or_b32_e32 v8, 0x180, v6
	v_add_u32_e32 v61, v4, v18
	v_or_b32_e32 v18, 0x380, v6
	v_add_u32_e32 v65, v4, v26
	v_or_b32_e32 v26, 0x580, v6
	v_add_u32_e32 v69, v4, v34
	v_or_b32_e32 v34, 0x780, v6
	v_lshrrev_b32_e32 v8, 1, v8
	v_lshrrev_b32_e32 v18, 1, v18
	v_lshrrev_b32_e32 v26, 1, v26
	v_lshrrev_b32_e32 v34, 1, v34
	v_and_b32_e32 v8, 0xf8, v8
	v_and_b32_e32 v18, 0x1f8, v18
	v_and_b32_e32 v26, 0x2f8, v26
	v_and_b32_e32 v34, 0x3f8, v34
	s_waitcnt lgkmcnt(0)
	s_barrier
	v_add_u32_e32 v58, v4, v8
	ds_read_b64 v[8:9], v17
	ds_read_b64 v[10:11], v56 offset:1024
	ds_read_b64 v[12:13], v57 offset:2048
	ds_read_b64 v[14:15], v58 offset:3072
	v_add_u32_e32 v62, v4, v18
	ds_read_b64 v[18:19], v59 offset:4096
	ds_read_b64 v[20:21], v60 offset:5120
	ds_read_b64 v[22:23], v61 offset:6144
	ds_read_b64 v[24:25], v62 offset:7168
	v_add_u32_e32 v66, v4, v26
	ds_read_b64 v[26:27], v63 offset:8192
	ds_read_b64 v[28:29], v64 offset:9216
	ds_read_b64 v[30:31], v65 offset:10240
	ds_read_b64 v[32:33], v66 offset:11264
	v_add_u32_e32 v70, v4, v34
	ds_read_b64 v[34:35], v67 offset:12288
	ds_read_b64 v[36:37], v68 offset:13312
	ds_read_b64 v[38:39], v69 offset:14336
	ds_read_b64 v[40:41], v70 offset:15360
	s_waitcnt lgkmcnt(7)
	v_pk_add_f32 v[42:43], v[8:9], v[26:27]
	v_pk_add_f32 v[8:9], v[8:9], v[26:27] neg_lo:[0,1] neg_hi:[0,1]
	s_waitcnt lgkmcnt(3)
	v_pk_add_f32 v[26:27], v[18:19], v[34:35]
	v_pk_add_f32 v[18:19], v[18:19], v[34:35] neg_lo:[0,1] neg_hi:[0,1]
	s_movk_i32 s2, 0x88
	v_xor_b32_e32 v35, 0x80000000, v18
	v_mov_b32_e32 v34, v19
	v_pk_add_f32 v[44:45], v[8:9], v[34:35]
	v_pk_add_f32 v[8:9], v[8:9], v[34:35] neg_lo:[0,1] neg_hi:[0,1]
	v_pk_add_f32 v[34:35], v[10:11], v[28:29]
	v_pk_add_f32 v[10:11], v[10:11], v[28:29] neg_lo:[0,1] neg_hi:[0,1]
	s_waitcnt lgkmcnt(2)
	v_pk_add_f32 v[28:29], v[20:21], v[36:37]
	v_pk_add_f32 v[20:21], v[20:21], v[36:37] neg_lo:[0,1] neg_hi:[0,1]
	v_pk_add_f32 v[18:19], v[42:43], v[26:27]
	v_xor_b32_e32 v37, 0x80000000, v20
	v_mov_b32_e32 v36, v21
	v_pk_add_f32 v[20:21], v[34:35], v[28:29]
	v_pk_add_f32 v[28:29], v[34:35], v[28:29] neg_lo:[0,1] neg_hi:[0,1]
	v_pk_add_f32 v[34:35], v[12:13], v[30:31]
	v_pk_add_f32 v[12:13], v[12:13], v[30:31] neg_lo:[0,1] neg_hi:[0,1]
	s_waitcnt lgkmcnt(1)
	v_pk_add_f32 v[30:31], v[22:23], v[38:39]
	v_pk_add_f32 v[22:23], v[22:23], v[38:39] neg_lo:[0,1] neg_hi:[0,1]
	v_pk_add_f32 v[26:27], v[42:43], v[26:27] neg_lo:[0,1] neg_hi:[0,1]
	v_pk_add_f32 v[42:43], v[10:11], v[36:37]
	v_pk_add_f32 v[10:11], v[10:11], v[36:37] neg_lo:[0,1] neg_hi:[0,1]
	v_xor_b32_e32 v37, 0x80000000, v22
	v_mov_b32_e32 v36, v23
	v_pk_add_f32 v[22:23], v[34:35], v[30:31]
	v_pk_add_f32 v[30:31], v[34:35], v[30:31] neg_lo:[0,1] neg_hi:[0,1]
	v_pk_add_f32 v[34:35], v[14:15], v[32:33]
	v_pk_add_f32 v[14:15], v[14:15], v[32:33] neg_lo:[0,1] neg_hi:[0,1]
	s_waitcnt lgkmcnt(0)
	v_pk_add_f32 v[32:33], v[24:25], v[40:41]
	v_pk_add_f32 v[24:25], v[24:25], v[40:41] neg_lo:[0,1] neg_hi:[0,1]
	v_pk_add_f32 v[38:39], v[12:13], v[36:37]
	v_pk_add_f32 v[12:13], v[12:13], v[36:37] neg_lo:[0,1] neg_hi:[0,1]
	v_xor_b32_e32 v37, 0x80000000, v24
	v_mov_b32_e32 v36, v25
	v_pk_add_f32 v[24:25], v[34:35], v[32:33]
	v_pk_add_f32 v[32:33], v[34:35], v[32:33] neg_lo:[0,1] neg_hi:[0,1]
	v_pk_mul_f32 v[34:35], v[42:43], s[70:71] op_sel_hi:[1,0]
	v_pk_add_f32 v[40:41], v[14:15], v[36:37]
	v_pk_add_f32 v[14:15], v[14:15], v[36:37] neg_lo:[0,1] neg_hi:[0,1]
	v_pk_fma_f32 v[36:37], v[42:43], s[68:69], v[34:35] op_sel:[0,0,1] op_sel_hi:[1,0,0]
	v_pk_fma_f32 v[34:35], v[42:43], s[68:69], v[34:35] op_sel:[0,0,1] op_sel_hi:[1,0,0] neg_lo:[0,0,1] neg_hi:[0,0,1]
	v_pk_mul_f32 v[48:49], v[12:13], s[8:9] op_sel_hi:[1,0]
	v_mov_b32_e32 v37, v35
	v_pk_mul_f32 v[34:35], v[28:29], s[18:19] op_sel_hi:[1,0]
	v_pk_fma_f32 v[50:51], v[12:13], s[8:9], v[48:49] op_sel:[0,0,1] op_sel_hi:[1,0,0] neg_lo:[0,0,1] neg_hi:[0,0,1]
	v_pk_fma_f32 v[12:13], v[12:13], s[8:9], v[48:49] op_sel_hi:[1,0,0]
	v_pk_mul_f32 v[48:49], v[40:41], s[68:69] op_sel_hi:[1,0]
	v_pk_fma_f32 v[42:43], v[28:29], s[18:19], v[34:35] op_sel:[0,0,1] op_sel_hi:[1,0,0]
	v_pk_fma_f32 v[28:29], v[28:29], s[18:19], v[34:35] op_sel_hi:[1,0,0] neg_lo:[0,0,1] neg_hi:[0,0,1]
	v_pk_mul_f32 v[34:35], v[10:11], s[68:69] op_sel_hi:[1,0]
	v_pk_fma_f32 v[52:53], v[40:41], s[70:71], v[48:49] op_sel:[0,0,1] op_sel_hi:[1,0,0]
	v_pk_fma_f32 v[40:41], v[40:41], s[70:71], v[48:49] op_sel:[0,0,1] op_sel_hi:[1,0,0] neg_lo:[0,0,1] neg_hi:[0,0,1]
	v_pk_fma_f32 v[46:47], v[10:11], s[70:71], v[34:35] op_sel:[0,0,1] op_sel_hi:[1,0,0]
	v_pk_fma_f32 v[10:11], v[10:11], s[70:71], v[34:35] op_sel:[0,0,1] op_sel_hi:[1,0,0] neg_lo:[0,0,1] neg_hi:[0,0,1]
	v_mov_b32_e32 v53, v41
	v_pk_mul_f32 v[40:41], v[32:33], s[8:9] op_sel_hi:[1,0]
	s_mov_b32 s71, s68
	v_mov_b32_e32 v47, v11
	v_pk_mul_f32 v[10:11], v[38:39], s[18:19] op_sel_hi:[1,0]
	v_pk_fma_f32 v[48:49], v[32:33], s[8:9], v[40:41] op_sel:[0,0,1] op_sel_hi:[1,0,0] neg_lo:[0,0,1] neg_hi:[0,0,1]
	v_pk_fma_f32 v[32:33], v[32:33], s[8:9], v[40:41] op_sel_hi:[1,0,0]
	v_pk_mul_f32 v[40:41], v[14:15], s[70:71] op_sel:[1,0]
	v_pk_fma_f32 v[34:35], v[38:39], s[18:19], v[10:11] op_sel:[0,0,1] op_sel_hi:[1,0,0]
	v_pk_fma_f32 v[10:11], v[38:39], s[18:19], v[10:11] op_sel_hi:[1,0,0] neg_lo:[0,0,1] neg_hi:[0,0,1]
	v_pk_fma_f32 v[14:15], v[14:15], s[4:5], v[40:41] op_sel_hi:[0,1,1] neg_lo:[0,0,1] neg_hi:[0,0,1]
	v_pk_add_f32 v[40:41], v[18:19], v[22:23]
	v_pk_add_f32 v[18:19], v[18:19], v[22:23] neg_lo:[0,1] neg_hi:[0,1]
	v_pk_add_f32 v[22:23], v[20:21], v[24:25]
	v_pk_add_f32 v[20:21], v[20:21], v[24:25] neg_lo:[0,1] neg_hi:[0,1]
	v_xor_b32_e32 v39, 0x80000000, v30
	v_xor_b32_e32 v25, 0x80000000, v20
	v_mov_b32_e32 v24, v21
	v_mov_b32_e32 v35, v11
	v_mov_b32_e32 v38, v31
	v_mov_b32_e32 v43, v29
	v_mov_b32_e32 v49, v33
	v_pk_add_f32 v[54:55], v[18:19], v[24:25]
	v_pk_add_f32 v[18:19], v[18:19], v[24:25] neg_lo:[0,1] neg_hi:[0,1]
	v_pk_add_f32 v[10:11], v[44:45], v[34:35]
	v_pk_add_f32 v[24:25], v[44:45], v[34:35] neg_lo:[0,1] neg_hi:[0,1]
	v_pk_add_f32 v[34:35], v[36:37], v[52:53]
	v_pk_add_f32 v[36:37], v[36:37], v[52:53] neg_lo:[0,1] neg_hi:[0,1]
	v_pk_add_f32 v[30:31], v[26:27], v[38:39]
	v_pk_add_f32 v[28:29], v[42:43], v[48:49]
	v_pk_add_f32 v[32:33], v[42:43], v[48:49] neg_lo:[0,1] neg_hi:[0,1]
	v_pk_add_f32 v[20:21], v[40:41], v[22:23]
	v_pk_add_f32 v[22:23], v[40:41], v[22:23] neg_lo:[0,1] neg_hi:[0,1]
	v_xor_b32_e32 v41, 0x80000000, v36
	v_mov_b32_e32 v40, v37
	v_pk_add_f32 v[36:37], v[10:11], v[34:35]
	v_pk_add_f32 v[10:11], v[10:11], v[34:35] neg_lo:[0,1] neg_hi:[0,1]
	v_pk_add_f32 v[26:27], v[26:27], v[38:39] neg_lo:[0,1] neg_hi:[0,1]
	v_xor_b32_e32 v35, 0x80000000, v32
	v_mov_b32_e32 v34, v33
	v_pk_add_f32 v[32:33], v[30:31], v[28:29]
	v_pk_add_f32 v[28:29], v[30:31], v[28:29] neg_lo:[0,1] neg_hi:[0,1]
	v_mov_b32_e32 v51, v13
	v_pk_add_f32 v[30:31], v[46:47], v[14:15]
	v_pk_add_f32 v[14:15], v[46:47], v[14:15] neg_lo:[0,1] neg_hi:[0,1]
	v_pk_add_f32 v[38:39], v[26:27], v[34:35]
	v_pk_add_f32 v[26:27], v[26:27], v[34:35] neg_lo:[0,1] neg_hi:[0,1]
	v_pk_add_f32 v[12:13], v[8:9], v[50:51]
	v_pk_add_f32 v[8:9], v[8:9], v[50:51] neg_lo:[0,1] neg_hi:[0,1]
	v_xor_b32_e32 v35, 0x80000000, v14
	v_mov_b32_e32 v34, v15
	v_pk_add_f32 v[44:45], v[24:25], v[40:41]
	v_pk_add_f32 v[24:25], v[24:25], v[40:41] neg_lo:[0,1] neg_hi:[0,1]
	v_pk_add_f32 v[40:41], v[8:9], v[34:35]
	v_pk_add_f32 v[8:9], v[8:9], v[34:35] neg_lo:[0,1] neg_hi:[0,1]
	v_mad_u32_u24 v4, v6, s2, v16
	v_and_b32_e32 v49, 15, v0
	v_pk_add_f32 v[14:15], v[12:13], v[30:31]
	v_pk_add_f32 v[12:13], v[12:13], v[30:31] neg_lo:[0,1] neg_hi:[0,1]
	s_barrier
	ds_write2_b64 v4, v[20:21], v[36:37] offset1:1
	ds_write2_b64 v4, v[32:33], v[14:15] offset0:2 offset1:3
	ds_write2_b64 v4, v[54:55], v[44:45] offset0:4 offset1:5
	ds_write2_b64 v4, v[38:39], v[40:41] offset0:6 offset1:7
	ds_write2_b64 v4, v[22:23], v[10:11] offset0:8 offset1:9
	ds_write2_b64 v4, v[28:29], v[12:13] offset0:10 offset1:11
	ds_write2_b64 v4, v[18:19], v[24:25] offset0:12 offset1:13
	ds_write2_b64 v4, v[26:27], v[8:9] offset0:14 offset1:15
	v_cvt_f32_ubyte0_e32 v8, v49
	s_waitcnt lgkmcnt(0)
	s_barrier
	v_mul_f32_e32 v9, 0x3b800000, v8
	ds_read_b64 v[10:11], v56 offset:1024
	v_sin_f32_e32 v12, v9
	v_cos_f32_e32 v8, v9
	ds_read_b64 v[18:19], v57 offset:2048
	ds_read_b64 v[20:21], v58 offset:3072
	ds_read_b64 v[14:15], v17
	v_lshlrev_b32_e32 v17, 2, v49
	s_waitcnt lgkmcnt(3)
	v_pk_mul_f32 v[22:23], v[12:13], v[10:11] op_sel:[0,1] op_sel_hi:[0,0]
	v_pk_fma_f32 v[12:13], v[8:9], v[10:11], v[22:23]
	v_lshlrev_b32_e32 v9, 1, v49
	v_cvt_f32_ubyte0_e32 v9, v9
	v_mul_f32_e32 v9, 0x3b800000, v9
	v_sin_f32_e32 v24, v9
	v_cos_f32_e32 v26, v9
	v_pk_fma_f32 v[8:9], v[8:9], v[10:11], v[22:23] op_sel_hi:[0,1,1] neg_lo:[0,0,1] neg_hi:[0,0,1]
	v_mov_b32_e32 v13, v9
	s_waitcnt lgkmcnt(2)
	v_pk_mul_f32 v[8:9], v[24:25], v[18:19] op_sel:[0,1] op_sel_hi:[0,0]
	v_pk_fma_f32 v[10:11], v[26:27], v[18:19], v[8:9]
	v_pk_fma_f32 v[8:9], v[26:27], v[18:19], v[8:9] op_sel_hi:[0,1,1] neg_lo:[0,0,1] neg_hi:[0,0,1]
	v_mul_u32_u24_e32 v11, 3, v49
	v_cvt_f32_ubyte0_e32 v11, v11
	v_mul_f32_e32 v11, 0x3b800000, v11
	v_sin_f32_e32 v22, v11
	v_cos_f32_e32 v24, v11
	v_cvt_f32_ubyte0_e32 v17, v17
	v_mov_b32_e32 v11, v9
	s_waitcnt lgkmcnt(1)
	v_pk_mul_f32 v[18:19], v[22:23], v[20:21] op_sel:[0,1] op_sel_hi:[0,0]
	v_pk_fma_f32 v[8:9], v[24:25], v[20:21], v[18:19]
	v_pk_fma_f32 v[18:19], v[24:25], v[20:21], v[18:19] op_sel_hi:[0,1,1] neg_lo:[0,0,1] neg_hi:[0,0,1]
	v_mul_f32_e32 v17, 0x3b800000, v17
	v_cos_f32_e32 v18, v17
	ds_read_b64 v[20:21], v59 offset:4096
	v_sin_f32_e32 v22, v17
	v_mul_u32_u24_e32 v17, 5, v49
	v_cvt_f32_ubyte0_e32 v17, v17
	v_mul_f32_e32 v17, 0x3b800000, v17
	v_sin_f32_e32 v32, v17
	ds_read_b64 v[24:25], v60 offset:5120
	ds_read_b64 v[26:27], v61 offset:6144
	ds_read_b64 v[28:29], v62 offset:7168
	v_cos_f32_e32 v34, v17
	v_mul_u32_u24_e32 v17, 6, v49
	s_waitcnt lgkmcnt(3)
	v_pk_mul_f32 v[22:23], v[22:23], v[20:21] op_sel:[0,1] op_sel_hi:[0,0]
	v_cvt_f32_ubyte0_e32 v17, v17
	v_mov_b32_e32 v9, v19
	v_pk_fma_f32 v[30:31], v[18:19], v[20:21], v[22:23]
	v_pk_fma_f32 v[18:19], v[18:19], v[20:21], v[22:23] op_sel_hi:[0,1,1] neg_lo:[0,0,1] neg_hi:[0,0,1]
	v_mul_f32_e32 v17, 0x3b800000, v17
	v_mov_b32_e32 v31, v19
	s_waitcnt lgkmcnt(2)
	v_pk_mul_f32 v[18:19], v[32:33], v[24:25] op_sel:[0,1] op_sel_hi:[0,0]
	v_sin_f32_e32 v22, v17
	v_cos_f32_e32 v32, v17
	v_mul_u32_u24_e32 v17, 7, v49
	v_cvt_f32_ubyte0_e32 v17, v17
	v_mul_f32_e32 v17, 0x3b800000, v17
	v_pk_fma_f32 v[20:21], v[34:35], v[24:25], v[18:19]
	v_pk_fma_f32 v[18:19], v[34:35], v[24:25], v[18:19] op_sel_hi:[0,1,1] neg_lo:[0,0,1] neg_hi:[0,0,1]
	v_sin_f32_e32 v24, v17
	v_cos_f32_e32 v34, v17
	v_mov_b32_e32 v21, v19
	s_waitcnt lgkmcnt(1)
	v_pk_mul_f32 v[18:19], v[22:23], v[26:27] op_sel:[0,1] op_sel_hi:[0,0]
	v_pk_fma_f32 v[22:23], v[32:33], v[26:27], v[18:19]
	v_pk_fma_f32 v[18:19], v[32:33], v[26:27], v[18:19] op_sel_hi:[0,1,1] neg_lo:[0,0,1] neg_hi:[0,0,1]
	v_mov_b32_e32 v23, v19
	s_waitcnt lgkmcnt(0)
	v_pk_mul_f32 v[18:19], v[24:25], v[28:29] op_sel:[0,1] op_sel_hi:[0,0]
	v_pk_fma_f32 v[24:25], v[34:35], v[28:29], v[18:19]
	v_pk_fma_f32 v[18:19], v[34:35], v[28:29], v[18:19] op_sel_hi:[0,1,1] neg_lo:[0,0,1] neg_hi:[0,0,1]
	v_lshlrev_b32_e32 v17, 3, v49
	v_cvt_f32_ubyte0_e32 v18, v17
	v_mov_b32_e32 v25, v19
	v_mul_f32_e32 v19, 0x3b800000, v18
	ds_read_b64 v[26:27], v63 offset:8192
	v_sin_f32_e32 v28, v19
	v_cos_f32_e32 v18, v19
	ds_read_b64 v[32:33], v64 offset:9216
	ds_read_b64 v[34:35], v65 offset:10240
	ds_read_b64 v[36:37], v66 offset:11264
	v_mul_u32_u24_e32 v4, 15, v49
	s_waitcnt lgkmcnt(3)
	v_pk_mul_f32 v[28:29], v[28:29], v[26:27] op_sel:[0,1] op_sel_hi:[0,0]
	v_pk_fma_f32 v[38:39], v[18:19], v[26:27], v[28:29]
	v_mul_u32_u24_e32 v19, 9, v49
	v_cvt_f32_ubyte0_e32 v19, v19
	v_mul_f32_e32 v19, 0x3b800000, v19
	v_sin_f32_e32 v40, v19
	v_cos_f32_e32 v42, v19
	v_pk_fma_f32 v[18:19], v[18:19], v[26:27], v[28:29] op_sel_hi:[0,1,1] neg_lo:[0,0,1] neg_hi:[0,0,1]
	v_mov_b32_e32 v39, v19
	s_waitcnt lgkmcnt(2)
	v_pk_mul_f32 v[18:19], v[40:41], v[32:33] op_sel:[0,1] op_sel_hi:[0,0]
	v_pk_fma_f32 v[26:27], v[42:43], v[32:33], v[18:19]
	v_pk_fma_f32 v[18:19], v[42:43], v[32:33], v[18:19] op_sel_hi:[0,1,1] neg_lo:[0,0,1] neg_hi:[0,0,1]
	v_mul_u32_u24_e32 v27, 10, v49
	v_cvt_f32_ubyte0_e32 v27, v27
	v_mul_f32_e32 v27, 0x3b800000, v27
	v_sin_f32_e32 v28, v27
	v_cos_f32_e32 v40, v27
	v_mov_b32_e32 v27, v19
	v_cvt_f32_ubyte0_e32 v4, v4
	s_waitcnt lgkmcnt(1)
	v_pk_mul_f32 v[18:19], v[28:29], v[34:35] op_sel:[0,1] op_sel_hi:[0,0]
	v_pk_fma_f32 v[28:29], v[40:41], v[34:35], v[18:19]
	v_pk_fma_f32 v[18:19], v[40:41], v[34:35], v[18:19] op_sel_hi:[0,1,1] neg_lo:[0,0,1] neg_hi:[0,0,1]
	v_mul_u32_u24_e32 v29, 11, v49
	v_cvt_f32_ubyte0_e32 v29, v29
	v_mul_f32_e32 v29, 0x3b800000, v29
	v_sin_f32_e32 v32, v29
	v_cos_f32_e32 v42, v29
	v_mov_b32_e32 v29, v19
	ds_read_b64 v[34:35], v67 offset:12288
	s_waitcnt lgkmcnt(1)
	v_pk_mul_f32 v[18:19], v[32:33], v[36:37] op_sel:[0,1] op_sel_hi:[0,0]
	v_pk_fma_f32 v[32:33], v[42:43], v[36:37], v[18:19]
	v_pk_fma_f32 v[18:19], v[42:43], v[36:37], v[18:19] op_sel_hi:[0,1,1] neg_lo:[0,0,1] neg_hi:[0,0,1]
	v_mul_u32_u24_e32 v18, 12, v49
	v_cvt_f32_ubyte0_e32 v18, v18
	v_mov_b32_e32 v33, v19
	v_mul_f32_e32 v19, 0x3b800000, v18
	v_sin_f32_e32 v36, v19
	v_cos_f32_e32 v18, v19
	ds_read_b64 v[40:41], v70 offset:15360
	ds_read_b64 v[42:43], v68 offset:13312
	ds_read_b64 v[44:45], v69 offset:14336
	v_mul_f32_e32 v6, 0x3b800000, v4
	s_waitcnt lgkmcnt(3)
	v_pk_mul_f32 v[36:37], v[36:37], v[34:35] op_sel:[0,1] op_sel_hi:[0,0]
	v_pk_fma_f32 v[46:47], v[18:19], v[34:35], v[36:37]
	v_mul_u32_u24_e32 v19, 13, v49
	v_cvt_f32_ubyte0_e32 v19, v19
	v_mul_f32_e32 v19, 0x3b800000, v19
	v_sin_f32_e32 v48, v19
	v_cos_f32_e32 v50, v19
	v_pk_fma_f32 v[18:19], v[18:19], v[34:35], v[36:37] op_sel_hi:[0,1,1] neg_lo:[0,0,1] neg_hi:[0,0,1]
	v_mov_b32_e32 v47, v19
	s_waitcnt lgkmcnt(1)
	v_pk_mul_f32 v[18:19], v[48:49], v[42:43] op_sel:[0,1] op_sel_hi:[0,0]
	v_pk_fma_f32 v[34:35], v[50:51], v[42:43], v[18:19]
	v_cos_f32_e32 v4, v6
	v_mul_u32_u24_e32 v35, 14, v49
	v_cvt_f32_ubyte0_e32 v35, v35
	v_mul_f32_e32 v35, 0x3b800000, v35
	v_sin_f32_e32 v36, v35
	v_cos_f32_e32 v48, v35
	v_sin_f32_e32 v6, v6
	v_pk_fma_f32 v[18:19], v[50:51], v[42:43], v[18:19] op_sel_hi:[0,1,1] neg_lo:[0,0,1] neg_hi:[0,0,1]
	v_mov_b32_e32 v35, v19
	s_waitcnt lgkmcnt(0)
	v_pk_mul_f32 v[18:19], v[36:37], v[44:45] op_sel:[0,1] op_sel_hi:[0,0]
	v_pk_fma_f32 v[36:37], v[48:49], v[44:45], v[18:19]
	v_pk_fma_f32 v[18:19], v[48:49], v[44:45], v[18:19] op_sel_hi:[0,1,1] neg_lo:[0,0,1] neg_hi:[0,0,1]
	v_mov_b32_e32 v37, v19
	v_pk_mul_f32 v[18:19], v[6:7], v[40:41] op_sel:[0,1] op_sel_hi:[0,0]
	v_pk_fma_f32 v[42:43], v[4:5], v[40:41], v[18:19]
	v_pk_fma_f32 v[18:19], v[4:5], v[40:41], v[18:19] op_sel_hi:[0,1,1] neg_lo:[0,0,1] neg_hi:[0,0,1]
	v_mov_b32_e32 v43, v19
	v_pk_add_f32 v[18:19], v[14:15], v[38:39]
	v_pk_add_f32 v[14:15], v[14:15], v[38:39] neg_lo:[0,1] neg_hi:[0,1]
	v_pk_add_f32 v[38:39], v[30:31], v[46:47]
	v_pk_add_f32 v[30:31], v[30:31], v[46:47] neg_lo:[0,1] neg_hi:[0,1]
	v_and_b32_e32 v4, 0x70, v0
	v_xor_b32_e32 v41, 0x80000000, v30
	v_mov_b32_e32 v40, v31
	v_pk_add_f32 v[30:31], v[18:19], v[38:39]
	v_pk_add_f32 v[18:19], v[18:19], v[38:39] neg_lo:[0,1] neg_hi:[0,1]
	v_pk_add_f32 v[38:39], v[12:13], v[26:27]
	v_pk_add_f32 v[12:13], v[12:13], v[26:27] neg_lo:[0,1] neg_hi:[0,1]
	v_pk_add_f32 v[26:27], v[20:21], v[34:35]
	v_pk_add_f32 v[20:21], v[20:21], v[34:35] neg_lo:[0,1] neg_hi:[0,1]
	v_pk_add_f32 v[44:45], v[14:15], v[40:41]
	v_xor_b32_e32 v35, 0x80000000, v20
	v_mov_b32_e32 v34, v21
	v_pk_add_f32 v[14:15], v[14:15], v[40:41] neg_lo:[0,1] neg_hi:[0,1]
	v_pk_add_f32 v[40:41], v[12:13], v[34:35]
	v_pk_add_f32 v[12:13], v[12:13], v[34:35] neg_lo:[0,1] neg_hi:[0,1]
	v_pk_add_f32 v[34:35], v[10:11], v[28:29]
	v_pk_add_f32 v[10:11], v[10:11], v[28:29] neg_lo:[0,1] neg_hi:[0,1]
	v_pk_add_f32 v[28:29], v[22:23], v[36:37]
	v_pk_add_f32 v[22:23], v[22:23], v[36:37] neg_lo:[0,1] neg_hi:[0,1]
	v_pk_add_f32 v[20:21], v[38:39], v[26:27]
	v_xor_b32_e32 v37, 0x80000000, v22
	v_mov_b32_e32 v36, v23
	v_pk_add_f32 v[22:23], v[34:35], v[28:29]
	v_pk_add_f32 v[28:29], v[34:35], v[28:29] neg_lo:[0,1] neg_hi:[0,1]
	v_pk_add_f32 v[34:35], v[8:9], v[32:33]
	v_pk_add_f32 v[8:9], v[8:9], v[32:33] neg_lo:[0,1] neg_hi:[0,1]
	v_pk_add_f32 v[32:33], v[42:43], v[24:25]
	v_pk_add_f32 v[24:25], v[24:25], v[42:43] neg_lo:[0,1] neg_hi:[0,1]
	v_pk_add_f32 v[26:27], v[38:39], v[26:27] neg_lo:[0,1] neg_hi:[0,1]
	v_pk_add_f32 v[38:39], v[10:11], v[36:37]
	v_pk_add_f32 v[10:11], v[10:11], v[36:37] neg_lo:[0,1] neg_hi:[0,1]
	v_xor_b32_e32 v37, 0x80000000, v24
	v_mov_b32_e32 v36, v25
	v_pk_add_f32 v[24:25], v[32:33], v[34:35]
	v_pk_add_f32 v[32:33], v[34:35], v[32:33] neg_lo:[0,1] neg_hi:[0,1]
	v_pk_mul_f32 v[34:35], v[40:41], s[70:71] op_sel_hi:[1,0]
	v_pk_add_f32 v[42:43], v[36:37], v[8:9]
	v_pk_add_f32 v[8:9], v[8:9], v[36:37] neg_lo:[0,1] neg_hi:[0,1]
	v_pk_fma_f32 v[36:37], v[40:41], s[68:69], v[34:35] op_sel:[0,0,1] op_sel_hi:[1,0,0]
	v_pk_fma_f32 v[34:35], v[40:41], s[68:69], v[34:35] op_sel:[0,0,1] op_sel_hi:[1,0,0] neg_lo:[0,0,1] neg_hi:[0,0,1]
	v_pk_mul_f32 v[48:49], v[10:11], s[8:9] op_sel_hi:[1,0]
	v_mov_b32_e32 v37, v35
	v_pk_mul_f32 v[34:35], v[26:27], s[18:19] op_sel_hi:[1,0]
	v_pk_fma_f32 v[50:51], v[10:11], s[8:9], v[48:49] op_sel:[0,0,1] op_sel_hi:[1,0,0] neg_lo:[0,0,1] neg_hi:[0,0,1]
	v_pk_fma_f32 v[10:11], v[10:11], s[8:9], v[48:49] op_sel_hi:[1,0,0]
	v_pk_mul_f32 v[48:49], v[42:43], s[68:69] op_sel_hi:[1,0]
	v_pk_fma_f32 v[40:41], v[26:27], s[18:19], v[34:35] op_sel:[0,0,1] op_sel_hi:[1,0,0]
	v_pk_fma_f32 v[26:27], v[26:27], s[18:19], v[34:35] op_sel_hi:[1,0,0] neg_lo:[0,0,1] neg_hi:[0,0,1]
	v_pk_mul_f32 v[34:35], v[12:13], s[68:69] op_sel_hi:[1,0]
	v_pk_fma_f32 v[52:53], v[42:43], s[70:71], v[48:49] op_sel:[0,0,1] op_sel_hi:[1,0,0]
	v_pk_fma_f32 v[42:43], v[42:43], s[70:71], v[48:49] op_sel:[0,0,1] op_sel_hi:[1,0,0] neg_lo:[0,0,1] neg_hi:[0,0,1]
	v_pk_fma_f32 v[46:47], v[12:13], s[70:71], v[34:35] op_sel:[0,0,1] op_sel_hi:[1,0,0]
	v_pk_fma_f32 v[12:13], v[12:13], s[70:71], v[34:35] op_sel:[0,0,1] op_sel_hi:[1,0,0] neg_lo:[0,0,1] neg_hi:[0,0,1]
	v_mov_b32_e32 v53, v43
	v_pk_mul_f32 v[42:43], v[32:33], s[8:9] op_sel_hi:[1,0]
	v_mov_b32_e32 v47, v13
	v_pk_mul_f32 v[12:13], v[38:39], s[18:19] op_sel_hi:[1,0]
	v_pk_fma_f32 v[48:49], v[32:33], s[8:9], v[42:43] op_sel:[0,0,1] op_sel_hi:[1,0,0] neg_lo:[0,0,1] neg_hi:[0,0,1]
	v_pk_fma_f32 v[32:33], v[32:33], s[8:9], v[42:43] op_sel_hi:[1,0,0]
	v_pk_mul_f32 v[42:43], v[8:9], s[70:71] op_sel:[1,0]
	v_pk_fma_f32 v[34:35], v[38:39], s[18:19], v[12:13] op_sel:[0,0,1] op_sel_hi:[1,0,0]
	v_pk_fma_f32 v[12:13], v[38:39], s[18:19], v[12:13] op_sel_hi:[1,0,0] neg_lo:[0,0,1] neg_hi:[0,0,1]
	v_pk_fma_f32 v[8:9], v[8:9], s[4:5], v[42:43] op_sel_hi:[0,1,1] neg_lo:[0,0,1] neg_hi:[0,0,1]
	v_pk_add_f32 v[42:43], v[30:31], v[22:23]
	v_pk_add_f32 v[22:23], v[30:31], v[22:23] neg_lo:[0,1] neg_hi:[0,1]
	v_pk_add_f32 v[30:31], v[24:25], v[20:21]
	v_pk_add_f32 v[20:21], v[20:21], v[24:25] neg_lo:[0,1] neg_hi:[0,1]
	v_xor_b32_e32 v39, 0x80000000, v28
	v_xor_b32_e32 v25, 0x80000000, v20
	v_mov_b32_e32 v24, v21
	v_mov_b32_e32 v35, v13
	v_mov_b32_e32 v38, v29
	v_mov_b32_e32 v41, v27
	v_mov_b32_e32 v49, v33
	v_pk_add_f32 v[54:55], v[22:23], v[24:25]
	v_pk_add_f32 v[22:23], v[22:23], v[24:25] neg_lo:[0,1] neg_hi:[0,1]
	v_pk_add_f32 v[12:13], v[44:45], v[34:35]
	v_pk_add_f32 v[24:25], v[44:45], v[34:35] neg_lo:[0,1] neg_hi:[0,1]
	v_pk_add_f32 v[34:35], v[52:53], v[36:37]
	v_pk_add_f32 v[36:37], v[36:37], v[52:53] neg_lo:[0,1] neg_hi:[0,1]
	v_pk_add_f32 v[28:29], v[18:19], v[38:39]
	v_pk_add_f32 v[26:27], v[48:49], v[40:41]
	v_pk_add_f32 v[32:33], v[40:41], v[48:49] neg_lo:[0,1] neg_hi:[0,1]
	v_pk_add_f32 v[20:21], v[30:31], v[42:43]
	v_pk_add_f32 v[30:31], v[42:43], v[30:31] neg_lo:[0,1] neg_hi:[0,1]
	v_xor_b32_e32 v43, 0x80000000, v36
	v_mov_b32_e32 v42, v37
	v_pk_add_f32 v[36:37], v[34:35], v[12:13]
	v_pk_add_f32 v[12:13], v[12:13], v[34:35] neg_lo:[0,1] neg_hi:[0,1]
	v_pk_add_f32 v[18:19], v[18:19], v[38:39] neg_lo:[0,1] neg_hi:[0,1]
	v_xor_b32_e32 v35, 0x80000000, v32
	v_mov_b32_e32 v34, v33
	v_pk_add_f32 v[32:33], v[28:29], v[26:27]
	v_pk_add_f32 v[26:27], v[28:29], v[26:27] neg_lo:[0,1] neg_hi:[0,1]
	v_mov_b32_e32 v51, v11
	v_pk_add_f32 v[28:29], v[8:9], v[46:47]
	v_pk_add_f32 v[8:9], v[46:47], v[8:9] neg_lo:[0,1] neg_hi:[0,1]
	v_add_u32_e32 v6, v16, v17
	v_lshlrev_b32_e32 v16, 7, v4
	v_lshlrev_b32_e32 v4, 3, v4
	v_pk_add_f32 v[38:39], v[18:19], v[34:35]
	v_pk_add_f32 v[18:19], v[18:19], v[34:35] neg_lo:[0,1] neg_hi:[0,1]
	v_pk_add_f32 v[10:11], v[14:15], v[50:51]
	v_pk_add_f32 v[14:15], v[14:15], v[50:51] neg_lo:[0,1] neg_hi:[0,1]
	v_xor_b32_e32 v35, 0x80000000, v8
	v_mov_b32_e32 v34, v9
	v_add3_u32 v4, v6, v16, v4
	v_pk_add_f32 v[44:45], v[24:25], v[42:43]
	v_pk_add_f32 v[24:25], v[24:25], v[42:43] neg_lo:[0,1] neg_hi:[0,1]
	v_pk_add_f32 v[8:9], v[28:29], v[10:11]
	v_pk_add_f32 v[40:41], v[14:15], v[34:35]
	v_pk_add_f32 v[10:11], v[10:11], v[28:29] neg_lo:[0,1] neg_hi:[0,1]
	v_pk_add_f32 v[14:15], v[14:15], v[34:35] neg_lo:[0,1] neg_hi:[0,1]
	s_barrier
	ds_write2_b64 v4, v[20:21], v[36:37] offset1:17
	ds_write2_b64 v4, v[32:33], v[8:9] offset0:34 offset1:51
	ds_write2_b64 v4, v[54:55], v[44:45] offset0:68 offset1:85
	ds_write2_b64 v4, v[38:39], v[40:41] offset0:102 offset1:119
	ds_write2_b64 v4, v[30:31], v[12:13] offset0:136 offset1:153
	ds_write2_b64 v4, v[26:27], v[10:11] offset0:170 offset1:187
	ds_write2_b64 v4, v[22:23], v[24:25] offset0:204 offset1:221
	ds_write2_b64 v4, v[18:19], v[14:15] offset0:238 offset1:255
	v_or_b32_sdwa v4, v0, s79 dst_sel:DWORD dst_unused:UNUSED_PAD src0_sel:BYTE_0 src1_sel:DWORD
	v_lshrrev_b32_e32 v4, 1, v4
	v_add3_u32 v7, 0, v7, v1
	v_and_b32_e32 v27, 0xf8, v4
	v_add_u32_e32 v29, v7, v27
	v_cvt_f32_ubyte0_e32 v4, v0
	v_or_b32_sdwa v10, v0, s78 dst_sel:DWORD dst_unused:UNUSED_PAD src0_sel:BYTE_0 src1_sel:DWORD
	s_waitcnt lgkmcnt(0)
	s_barrier
	ds_read_b64 v[8:9], v29 offset:2048
	v_mul_f32_e32 v6, 0x3a000000, v4
	v_lshrrev_b32_e32 v10, 1, v10
	v_cos_f32_e32 v4, v6
	v_sin_f32_e32 v6, v6
	v_and_b32_e32 v49, 0x178, v10
	v_lshlrev_b32_sdwa v10, v226, v0 dst_sel:DWORD dst_unused:UNUSED_PAD src0_sel:DWORD src1_sel:BYTE_0
	s_mov_b32 s2, s4
	v_cvt_f32_u32_e32 v20, v10
	v_writelane_b32 v254, s2, 16
	v_and_b32_e32 v5, 0x78, v5
	s_waitcnt lgkmcnt(0)
	v_pk_mul_f32 v[16:17], v[6:7], v[8:9] op_sel_hi:[0,1]
	v_writelane_b32 v254, s3, 17
	s_movk_i32 s2, 0x300
	v_or_b32_sdwa v10, v0, s2 dst_sel:DWORD dst_unused:UNUSED_PAD src0_sel:BYTE_0 src1_sel:DWORD
	v_lshrrev_b32_e32 v10, 1, v10
	v_pk_fma_f32 v[18:19], v[4:5], v[8:9], v[16:17] op_sel:[0,0,1] op_sel_hi:[1,1,0]
	v_pk_fma_f32 v[8:9], v[4:5], v[8:9], v[16:17] op_sel:[0,0,1] op_sel_hi:[0,1,0] neg_lo:[0,0,1] neg_hi:[0,0,1]
	v_mul_f32_e32 v16, 0x3a000000, v20
	v_mul_u32_u24_sdwa v17, v0, v230 dst_sel:DWORD dst_unused:UNUSED_PAD src0_sel:BYTE_0 src1_sel:DWORD
	v_add_u32_e32 v51, v7, v49
	v_and_b32_e32 v56, 0x1f8, v10
	v_cos_f32_e32 v8, v16
	v_sin_f32_e32 v16, v16
	v_cvt_f32_u32_e32 v17, v17
	v_add_u32_e32 v25, v7, v5
	v_add_u32_e32 v57, v7, v56
	ds_read_b64 v[10:11], v51 offset:4096
	ds_read_b64 v[12:13], v57 offset:6144
	ds_read_b64 v[14:15], v25
	v_mov_b32_e32 v19, v9
	s_movk_i32 s2, 0x400
	s_waitcnt lgkmcnt(2)
	v_pk_mul_f32 v[20:21], v[16:17], v[10:11] op_sel_hi:[0,1]
	v_pk_fma_f32 v[22:23], v[8:9], v[10:11], v[20:21] op_sel:[0,0,1] op_sel_hi:[1,1,0]
	v_mul_f32_e32 v9, 0x3a000000, v17
	v_sin_f32_e32 v24, v9
	v_cos_f32_e32 v26, v9
	v_pk_fma_f32 v[10:11], v[8:9], v[10:11], v[20:21] op_sel:[0,0,1] op_sel_hi:[0,1,0] neg_lo:[0,0,1] neg_hi:[0,0,1]
	v_mov_b32_e32 v23, v11
	s_waitcnt lgkmcnt(1)
	v_pk_mul_f32 v[10:11], v[24:25], v[12:13] op_sel_hi:[0,1]
	v_pk_fma_f32 v[20:21], v[26:27], v[12:13], v[10:11] op_sel:[0,0,1] op_sel_hi:[1,1,0]
	v_pk_fma_f32 v[10:11], v[26:27], v[12:13], v[10:11] op_sel:[0,0,1] op_sel_hi:[0,1,0] neg_lo:[0,0,1] neg_hi:[0,0,1]
	v_lshlrev_b32_sdwa v10, v233, v0 dst_sel:DWORD dst_unused:UNUSED_PAD src0_sel:DWORD src1_sel:BYTE_0
	v_or_b32_sdwa v9, v0, s2 dst_sel:DWORD dst_unused:UNUSED_PAD src0_sel:BYTE_0 src1_sel:DWORD
	v_cvt_f32_u32_e32 v12, v10
	v_lshrrev_b32_e32 v9, 1, v9
	v_and_b32_e32 v9, 0x278, v9
	v_add_u32_e32 v13, v7, v9
	v_mov_b32_e32 v21, v11
	ds_read_b64 v[10:11], v13 offset:8192
	v_mul_f32_e32 v17, 0x3a000000, v12
	v_sin_f32_e32 v28, v17
	v_cos_f32_e32 v12, v17
	v_mul_u32_u24_sdwa v38, v0, v234 dst_sel:DWORD dst_unused:UNUSED_PAD src0_sel:BYTE_0 src1_sel:DWORD
	s_movk_i32 s2, 0x500
	v_cvt_f32_u32_e32 v40, v38
	v_or_b32_sdwa v17, v0, s2 dst_sel:DWORD dst_unused:UNUSED_PAD src0_sel:BYTE_0 src1_sel:DWORD
	s_movk_i32 s2, 0x600
	v_or_b32_sdwa v30, v0, s2 dst_sel:DWORD dst_unused:UNUSED_PAD src0_sel:BYTE_0 src1_sel:DWORD
	s_waitcnt lgkmcnt(0)
	v_pk_mul_f32 v[36:37], v[28:29], v[10:11] op_sel_hi:[0,1]
	v_lshrrev_b32_e32 v30, 1, v30
	s_movk_i32 s2, 0x700
	v_pk_fma_f32 v[38:39], v[12:13], v[10:11], v[36:37] op_sel:[0,0,1] op_sel_hi:[1,1,0]
	v_pk_fma_f32 v[10:11], v[12:13], v[10:11], v[36:37] op_sel:[0,0,1] op_sel_hi:[0,1,0] neg_lo:[0,0,1] neg_hi:[0,0,1]
	v_lshrrev_b32_e32 v17, 1, v17
	v_and_b32_e32 v59, 0x378, v30
	v_or_b32_sdwa v30, v0, s2 dst_sel:DWORD dst_unused:UNUSED_PAD src0_sel:BYTE_0 src1_sel:DWORD
	v_mov_b32_e32 v39, v11
	v_mul_f32_e32 v11, 0x3a000000, v40
	v_and_b32_e32 v17, 0x2f8, v17
	v_lshrrev_b32_e32 v30, 1, v30
	v_sin_f32_e32 v10, v11
	v_cos_f32_e32 v36, v11
	v_mul_u32_u24_sdwa v11, v0, v232 dst_sel:DWORD dst_unused:UNUSED_PAD src0_sel:BYTE_0 src1_sel:DWORD
	v_add_u32_e32 v58, v7, v17
	v_and_b32_e32 v61, 0x3f8, v30
	v_cvt_f32_u32_e32 v11, v11
	v_add_u32_e32 v60, v7, v59
	v_add_u32_e32 v7, v7, v61
	ds_read_b64 v[30:31], v58 offset:10240
	ds_read_b64 v[32:33], v60 offset:12288
	ds_read_b64 v[34:35], v7 offset:14336
	v_add3_u32 v1, 0, v3, v1
	v_add_u32_e32 v3, v1, v5
	s_waitcnt lgkmcnt(2)
	v_pk_mul_f32 v[40:41], v[10:11], v[30:31] op_sel_hi:[0,1]
	v_pk_fma_f32 v[42:43], v[36:37], v[30:31], v[40:41] op_sel:[0,0,1] op_sel_hi:[1,1,0]
	v_pk_fma_f32 v[30:31], v[36:37], v[30:31], v[40:41] op_sel:[0,0,1] op_sel_hi:[0,1,0] neg_lo:[0,0,1] neg_hi:[0,0,1]
	v_mul_f32_e32 v11, 0x3a000000, v11
	v_cos_f32_e32 v30, v11
	v_sin_f32_e32 v40, v11
	v_mul_u32_u24_sdwa v11, v0, v235 dst_sel:DWORD dst_unused:UNUSED_PAD src0_sel:BYTE_0 src1_sel:DWORD
	v_cvt_f32_u32_e32 v11, v11
	v_mov_b32_e32 v43, v31
	s_waitcnt lgkmcnt(1)
	v_pk_mul_f32 v[44:45], v[40:41], v[32:33] op_sel_hi:[0,1]
	v_pk_fma_f32 v[46:47], v[30:31], v[32:33], v[44:45] op_sel:[0,0,1] op_sel_hi:[1,1,0]
	v_mul_f32_e32 v11, 0x3a000000, v11
	v_sin_f32_e32 v48, v11
	v_cos_f32_e32 v50, v11
	v_pk_fma_f32 v[32:33], v[30:31], v[32:33], v[44:45] op_sel:[0,0,1] op_sel_hi:[0,1,0] neg_lo:[0,0,1] neg_hi:[0,0,1]
	v_mov_b32_e32 v47, v33
	s_waitcnt lgkmcnt(0)
	v_pk_mul_f32 v[32:33], v[48:49], v[34:35] op_sel_hi:[0,1]
	v_pk_fma_f32 v[44:45], v[50:51], v[34:35], v[32:33] op_sel:[0,0,1] op_sel_hi:[1,1,0]
	v_pk_fma_f32 v[32:33], v[50:51], v[34:35], v[32:33] op_sel:[0,0,1] op_sel_hi:[0,1,0] neg_lo:[0,0,1] neg_hi:[0,0,1]
	v_pk_add_f32 v[34:35], v[18:19], v[42:43]
	v_pk_add_f32 v[18:19], v[18:19], v[42:43] neg_lo:[0,1] neg_hi:[0,1]
	v_mov_b32_e32 v45, v33
	v_pk_add_f32 v[32:33], v[14:15], v[38:39]
	v_pk_add_f32 v[14:15], v[14:15], v[38:39] neg_lo:[0,1] neg_hi:[0,1]
	v_pk_mul_f32 v[38:39], v[18:19], s[18:19] op_sel_hi:[1,0]
	v_pk_add_f32 v[54:55], v[20:21], v[44:45]
	v_pk_fma_f32 v[42:43], v[18:19], s[18:19], v[38:39] op_sel:[0,0,1] op_sel_hi:[1,0,0]
	v_pk_fma_f32 v[18:19], v[18:19], s[18:19], v[38:39] op_sel_hi:[1,0,0] neg_lo:[0,0,1] neg_hi:[0,0,1]
	v_pk_add_f32 v[20:21], v[20:21], v[44:45] neg_lo:[0,1] neg_hi:[0,1]
	v_pk_add_f32 v[52:53], v[22:23], v[46:47]
	v_mov_b32_e32 v43, v19
	v_pk_add_f32 v[18:19], v[22:23], v[46:47] neg_lo:[0,1] neg_hi:[0,1]
	v_pk_mul_f32 v[22:23], v[20:21], s[8:9] op_sel_hi:[1,0]
	v_add_u32_e32 v31, v1, v9
	v_pk_fma_f32 v[38:39], v[20:21], s[8:9], v[22:23] op_sel:[0,0,1] op_sel_hi:[1,0,0] neg_lo:[0,0,1] neg_hi:[0,0,1]
	v_pk_fma_f32 v[20:21], v[20:21], s[8:9], v[22:23] op_sel_hi:[1,0,0]
	v_pk_add_f32 v[22:23], v[32:33], v[52:53] neg_lo:[0,1] neg_hi:[0,1]
	v_mov_b32_e32 v39, v21
	v_xor_b32_e32 v21, 0x80000000, v18
	v_mov_b32_e32 v20, v19
	v_pk_add_f32 v[18:19], v[32:33], v[52:53]
	v_pk_add_f32 v[32:33], v[34:35], v[54:55]
	v_pk_add_f32 v[34:35], v[34:35], v[54:55] neg_lo:[0,1] neg_hi:[0,1]
	v_add_u32_e32 v37, v1, v17
	v_xor_b32_e32 v45, 0x80000000, v34
	v_mov_b32_e32 v44, v35
	v_pk_add_f32 v[34:35], v[18:19], v[32:33]
	v_pk_add_f32 v[18:19], v[18:19], v[32:33] neg_lo:[0,1] neg_hi:[0,1]
	v_pk_add_f32 v[32:33], v[14:15], v[20:21]
	v_pk_add_f32 v[14:15], v[14:15], v[20:21] neg_lo:[0,1] neg_hi:[0,1]
	v_pk_add_f32 v[20:21], v[42:43], v[38:39]
	v_pk_add_f32 v[38:39], v[42:43], v[38:39] neg_lo:[0,1] neg_hi:[0,1]
	v_pk_add_f32 v[46:47], v[22:23], v[44:45]
	v_xor_b32_e32 v43, 0x80000000, v38
	v_mov_b32_e32 v42, v39
	v_pk_add_f32 v[22:23], v[22:23], v[44:45] neg_lo:[0,1] neg_hi:[0,1]
	v_pk_add_f32 v[38:39], v[32:33], v[20:21]
	v_pk_add_f32 v[44:45], v[14:15], v[42:43]
	v_pk_add_f32 v[20:21], v[32:33], v[20:21] neg_lo:[0,1] neg_hi:[0,1]
	v_pk_add_f32 v[14:15], v[14:15], v[42:43] neg_lo:[0,1] neg_hi:[0,1]
	ds_write_b64 v25, v[34:35]
	ds_write_b64 v29, v[38:39] offset:2048
	ds_write_b64 v51, v[46:47] offset:4096
	ds_write_b64 v57, v[44:45] offset:6144
	ds_write_b64 v13, v[18:19] offset:8192
	ds_write_b64 v58, v[20:21] offset:10240
	ds_write_b64 v60, v[22:23] offset:12288
	ds_write_b64 v7, v[14:15] offset:14336
	v_add_u32_e32 v25, v1, v27
	v_add_u32_e32 v27, v1, v49
	v_add_u32_e32 v29, v1, v56
	v_add_u32_e32 v49, v1, v59
	v_add_u32_e32 v1, v1, v61
	ds_read_b64 v[14:15], v31 offset:8192
	ds_read_b64 v[18:19], v37 offset:10240
	ds_read_b64 v[20:21], v49 offset:12288
	ds_read_b64 v[22:23], v1 offset:14336
	ds_read_b64 v[32:33], v3
	ds_read_b64 v[34:35], v25 offset:2048
	ds_read_b64 v[38:39], v27 offset:4096
	ds_read_b64 v[42:43], v29 offset:6144
	s_waitcnt lgkmcnt(4)
	v_pk_mul_f32 v[44:45], v[48:49], v[22:23] op_sel_hi:[0,1]
	v_pk_fma_f32 v[46:47], v[50:51], v[22:23], v[44:45] op_sel:[0,0,1] op_sel_hi:[1,1,0]
	v_pk_fma_f32 v[22:23], v[50:51], v[22:23], v[44:45] op_sel:[0,0,1] op_sel_hi:[0,1,0] neg_lo:[0,0,1] neg_hi:[0,0,1]
	v_mov_b32_e32 v47, v23
	v_pk_mul_f32 v[22:23], v[40:41], v[20:21] op_sel_hi:[0,1]
	v_pk_fma_f32 v[40:41], v[30:31], v[20:21], v[22:23] op_sel:[0,0,1] op_sel_hi:[1,1,0]
	v_pk_fma_f32 v[20:21], v[30:31], v[20:21], v[22:23] op_sel:[0,0,1] op_sel_hi:[0,1,0] neg_lo:[0,0,1] neg_hi:[0,0,1]
	v_pk_mul_f32 v[10:11], v[10:11], v[18:19] op_sel_hi:[0,1]
	v_mov_b32_e32 v41, v21
	v_pk_fma_f32 v[20:21], v[36:37], v[18:19], v[10:11] op_sel:[0,0,1] op_sel_hi:[1,1,0]
	v_pk_fma_f32 v[10:11], v[36:37], v[18:19], v[10:11] op_sel:[0,0,1] op_sel_hi:[0,1,0] neg_lo:[0,0,1] neg_hi:[0,0,1]
	v_mov_b32_e32 v21, v11
	v_pk_mul_f32 v[10:11], v[28:29], v[14:15] op_sel_hi:[0,1]
	v_pk_fma_f32 v[18:19], v[12:13], v[14:15], v[10:11] op_sel:[0,0,1] op_sel_hi:[1,1,0]
	v_pk_fma_f32 v[10:11], v[12:13], v[14:15], v[10:11] op_sel:[0,0,1] op_sel_hi:[0,1,0] neg_lo:[0,0,1] neg_hi:[0,0,1]
	v_mov_b32_e32 v19, v11
	s_waitcnt lgkmcnt(0)
	v_pk_mul_f32 v[10:11], v[24:25], v[42:43] op_sel_hi:[0,1]
	v_pk_fma_f32 v[12:13], v[26:27], v[42:43], v[10:11] op_sel:[0,0,1] op_sel_hi:[1,1,0]
	v_pk_fma_f32 v[10:11], v[26:27], v[42:43], v[10:11] op_sel:[0,0,1] op_sel_hi:[0,1,0] neg_lo:[0,0,1] neg_hi:[0,0,1]
	v_mov_b32_e32 v13, v11
	v_pk_mul_f32 v[10:11], v[16:17], v[38:39] op_sel_hi:[0,1]
	v_pk_fma_f32 v[14:15], v[8:9], v[38:39], v[10:11] op_sel:[0,0,1] op_sel_hi:[1,1,0]
	v_pk_fma_f32 v[8:9], v[8:9], v[38:39], v[10:11] op_sel:[0,0,1] op_sel_hi:[0,1,0] neg_lo:[0,0,1] neg_hi:[0,0,1]
	v_pk_mul_f32 v[6:7], v[6:7], v[34:35] op_sel_hi:[0,1]
	v_mov_b32_e32 v15, v9
	v_pk_fma_f32 v[8:9], v[4:5], v[34:35], v[6:7] op_sel:[0,0,1] op_sel_hi:[1,1,0]
	v_pk_fma_f32 v[4:5], v[4:5], v[34:35], v[6:7] op_sel:[0,0,1] op_sel_hi:[0,1,0] neg_lo:[0,0,1] neg_hi:[0,0,1]
	v_mov_b32_e32 v9, v5
	v_pk_add_f32 v[6:7], v[8:9], v[20:21]
	v_pk_add_f32 v[8:9], v[8:9], v[20:21] neg_lo:[0,1] neg_hi:[0,1]
	v_pk_add_f32 v[16:17], v[12:13], v[46:47]
	v_pk_mul_f32 v[20:21], v[8:9], s[18:19] op_sel_hi:[1,0]
	v_pk_add_f32 v[12:13], v[12:13], v[46:47] neg_lo:[0,1] neg_hi:[0,1]
	v_pk_fma_f32 v[22:23], v[8:9], s[18:19], v[20:21] op_sel:[0,0,1] op_sel_hi:[1,0,0]
	v_pk_fma_f32 v[8:9], v[8:9], s[18:19], v[20:21] op_sel_hi:[1,0,0] neg_lo:[0,0,1] neg_hi:[0,0,1]
	v_pk_add_f32 v[10:11], v[14:15], v[40:41]
	v_mov_b32_e32 v23, v9
	v_pk_add_f32 v[8:9], v[14:15], v[40:41] neg_lo:[0,1] neg_hi:[0,1]
	v_pk_mul_f32 v[14:15], v[12:13], s[8:9] op_sel_hi:[1,0]
	v_pk_add_f32 v[4:5], v[32:33], v[18:19]
	v_pk_fma_f32 v[20:21], v[12:13], s[8:9], v[14:15] op_sel:[0,0,1] op_sel_hi:[1,0,0] neg_lo:[0,0,1] neg_hi:[0,0,1]
	v_pk_fma_f32 v[12:13], v[12:13], s[8:9], v[14:15] op_sel_hi:[1,0,0]
	v_pk_add_f32 v[18:19], v[32:33], v[18:19] neg_lo:[0,1] neg_hi:[0,1]
	v_mov_b32_e32 v21, v13
	v_xor_b32_e32 v13, 0x80000000, v8
	v_mov_b32_e32 v12, v9
	v_pk_add_f32 v[8:9], v[4:5], v[10:11]
	v_pk_add_f32 v[4:5], v[4:5], v[10:11] neg_lo:[0,1] neg_hi:[0,1]
	v_pk_add_f32 v[10:11], v[6:7], v[16:17]
	v_pk_add_f32 v[6:7], v[6:7], v[16:17] neg_lo:[0,1] neg_hi:[0,1]
	v_readlane_b32 s2, v253, 9
	v_xor_b32_e32 v15, 0x80000000, v6
	v_mov_b32_e32 v14, v7
	v_pk_add_f32 v[6:7], v[8:9], v[10:11]
	v_pk_add_f32 v[8:9], v[8:9], v[10:11] neg_lo:[0,1] neg_hi:[0,1]
	v_pk_add_f32 v[10:11], v[18:19], v[12:13]
	v_pk_add_f32 v[12:13], v[18:19], v[12:13] neg_lo:[0,1] neg_hi:[0,1]
	v_pk_add_f32 v[18:19], v[22:23], v[20:21] neg_lo:[0,1] neg_hi:[0,1]
	v_pk_add_f32 v[16:17], v[4:5], v[14:15]
	v_pk_add_f32 v[4:5], v[4:5], v[14:15] neg_lo:[0,1] neg_hi:[0,1]
	v_pk_add_f32 v[14:15], v[22:23], v[20:21]
	v_xor_b32_e32 v21, 0x80000000, v18
	v_mov_b32_e32 v20, v19
	v_pk_add_f32 v[22:23], v[12:13], v[20:21]
	v_pk_add_f32 v[12:13], v[12:13], v[20:21] neg_lo:[0,1] neg_hi:[0,1]
	v_pk_add_f32 v[18:19], v[10:11], v[14:15]
	v_pk_add_f32 v[10:11], v[10:11], v[14:15] neg_lo:[0,1] neg_hi:[0,1]
	ds_write_b64 v3, v[6:7]
	ds_write_b64 v25, v[18:19] offset:2048
	ds_write_b64 v27, v[16:17] offset:4096
	ds_write_b64 v29, v[22:23] offset:6144
	ds_write_b64 v31, v[8:9] offset:8192
	ds_write_b64 v37, v[10:11] offset:10240
	ds_write_b64 v49, v[4:5] offset:12288
	ds_write_b64 v1, v[12:13] offset:14336
	v_ashrrev_i32_e32 v1, 4, v0
	v_lshl_add_u32 v12, v0, 3, 0
	v_lshl_add_u32 v1, v1, 3, v12
	s_waitcnt lgkmcnt(0)
	s_barrier
	ds_read2st64_b64 v[4:7], v1 offset1:34
	s_add_u32 s1, s2, s1
	v_readlane_b32 s2, v253, 10
	s_addc_u32 s2, s2, 0
	s_lshl_b32 s0, s0, 1
	s_waitcnt lgkmcnt(0)
	v_mul_f32_e32 v3, 0x3cb504f3, v4
	v_mul_f32_e32 v4, 0x3cb504f3, v6
	v_cvt_pk_bf16_f32 v8, v3, v4
	ds_read2st64_b64 v[4:7], v1 offset0:68 offset1:102
	s_add_u32 s0, s1, s0
	s_addc_u32 s1, s2, 0
	s_waitcnt lgkmcnt(0)
	v_mul_f32_e32 v1, 0x3cb504f3, v4
	v_mul_f32_e32 v3, 0x3cb504f3, v6
	v_cvt_pk_bf16_f32 v9, v1, v3
	v_ashrrev_i32_e32 v1, 4, v2
	v_lshl_add_u32 v3, v1, 3, v12
	ds_read2st64_b64 v[4:7], v3 offset0:8 offset1:42
	v_ashrrev_i32_e32 v1, 31, v0
	v_lshlrev_b64 v[10:11], 12, v[0:1]
	v_lshl_add_u64 v[10:11], s[0:1], 0, v[10:11]
	global_store_dwordx2 v[10:11], v[8:9], off
	s_waitcnt lgkmcnt(0)
	v_mul_f32_e32 v1, 0x3cb504f3, v4
	v_mul_f32_e32 v4, 0x3cb504f3, v6
	v_cvt_pk_bf16_f32 v8, v1, v4
	ds_read2st64_b64 v[4:7], v3 offset0:76 offset1:110
	v_add_u32_e32 v10, 0x400, v0
	v_ashrrev_i32_e32 v11, 31, v10
	s_waitcnt lgkmcnt(0)
	v_mul_f32_e32 v1, 0x3cb504f3, v4
	v_mul_f32_e32 v3, 0x3cb504f3, v6
	v_cvt_pk_bf16_f32 v9, v1, v3
	v_ashrrev_i32_e32 v1, 4, v10
	v_lshl_add_u32 v1, v1, 3, v12
	ds_read2st64_b64 v[4:7], v1 offset0:16 offset1:50
	v_ashrrev_i32_e32 v3, 31, v2
	v_lshlrev_b64 v[2:3], 12, v[2:3]
	v_lshl_add_u64 v[2:3], s[0:1], 0, v[2:3]
	global_store_dwordx2 v[2:3], v[8:9], off
	s_waitcnt lgkmcnt(0)
	v_mul_f32_e32 v2, 0x3cb504f3, v4
	v_mul_f32_e32 v3, 0x3cb504f3, v6
	v_cvt_pk_bf16_f32 v6, v2, v3
	ds_read2st64_b64 v[2:5], v1 offset0:84 offset1:118
	v_lshlrev_b64 v[8:9], 12, v[10:11]
	v_lshl_add_u64 v[8:9], s[0:1], 0, v[8:9]
	s_waitcnt lgkmcnt(0)
	v_mul_f32_e32 v1, 0x3cb504f3, v2
	v_mul_f32_e32 v2, 0x3cb504f3, v4
	v_add_u32_e32 v4, 0x600, v0
	v_ashrrev_i32_e32 v0, 4, v4
	v_lshl_add_u32 v5, v0, 3, v12
	v_cvt_pk_bf16_f32 v7, v1, v2
	ds_read2st64_b64 v[0:3], v5 offset0:24 offset1:58
	global_store_dwordx2 v[8:9], v[6:7], off
	s_waitcnt lgkmcnt(0)
	v_mul_f32_e32 v0, 0x3cb504f3, v0
	v_mul_f32_e32 v1, 0x3cb504f3, v2
	v_cvt_pk_bf16_f32 v6, v0, v1
	ds_read2st64_b64 v[0:3], v5 offset0:92 offset1:126
	v_ashrrev_i32_e32 v5, 31, v4
	s_waitcnt lgkmcnt(0)
	v_mul_f32_e32 v0, 0x3cb504f3, v0
	v_mul_f32_e32 v1, 0x3cb504f3, v2
	v_cvt_pk_bf16_f32 v7, v0, v1
	v_lshlrev_b64 v[0:1], 12, v[4:5]
	v_lshl_add_u64 v[0:1], s[0:1], 0, v[0:1]
	global_store_dwordx2 v[0:1], v[6:7], off
	s_barrier

.LBB0_206:
	s_andn2_b64 vcc, exec, s[0:1]
	s_cbranch_vccnz .LBB0_149
	v_mov_b32_e32 v20, v224
	s_ashr_i32 s2, s41, 4
	s_lshl_b32 s1, s41, 7
	v_readfirstlane_b32 s31, v20
	s_bfe_u32 s58, s31, 0x20006
	s_lshl_b32 s0, s2, 11
	s_and_b32 s1, s1, 0x780
	s_or_b32 s0, s0, s1
	s_lshl_b32 s1, s58, 5
	v_and_b32_e32 v21, 31, v20
	s_or_b32 s0, s1, s0
	v_or_b32_e32 v160, s0, v21
	s_ashr_i32 s59, s31, 8
	v_ashrrev_i32_e32 v161, 31, v160
	v_lshlrev_b64 v[0:1], 11, v[160:161]
	s_lshl_b32 s0, s59, 6
	v_bfe_u32 v163, v20, 5, 1
	v_lshl_add_u64 v[0:1], s[34:35], 0, v[0:1]
	s_ashr_i32 s1, s0, 31
	v_lshl_add_u64 v[0:1], s[0:1], 1, v[0:1]
	v_lshlrev_b32_e32 v192, 4, v163
	v_lshl_add_u64 v[0:1], v[0:1], 0, v[192:193]
	global_load_dwordx4 v[112:115], v[0:1], off nt
	global_load_dwordx4 v[116:119], v[0:1], off offset:32 nt
	global_load_dwordx4 v[120:123], v[0:1], off offset:64 nt
	s_lshl_b32 s0, s2, 3
	global_load_dwordx4 v[124:127], v[0:1], off offset:96 nt
	s_or_b32 s0, s0, s54
	s_lshl_b32 s1, s0, 1
	s_mul_i32 s4, s0, 0x90000
	s_mul_hi_i32 s1, s1, 0x48000
	s_add_u32 s2, s56, s4
	s_addc_u32 s3, s57, s1
	s_mul_hi_i32 s0, s0, 0x90000
	s_add_u32 s48, s44, s4
	s_addc_u32 s49, s45, s0
	s_add_u32 s62, s2, 0x48000
	s_addc_u32 s63, s3, 0
	s_add_u32 s4, s48, 0x48000
	s_addc_u32 s5, s49, 0
	s_and_b32 s0, s41, -16
	s_add_i32 s0, s0, s75
	s_add_i32 s0, s0, s59
	s_ashr_i32 s1, s0, 31
	v_ashrrev_i32_e32 v2, 3, v20
	v_and_b32_e32 v3, 7, v20
	s_lshl_b64 s[0:1], s[0:1], 2
	v_readlane_b32 s9, v252, 46
	v_lshlrev_b32_e32 v165, 7, v2
	v_lshlrev_b32_e32 v3, 4, v3
	s_add_u32 s0, s9, s0
	v_readlane_b32 s9, v252, 47
	v_or_b32_e32 v26, v165, v3
	s_addc_u32 s1, s9, s1
	global_load_dwordx4 v[128:131], v26, s[2:3]
	global_load_dwordx4 v[132:135], v26, s[62:63]
	global_load_dword v27, v193, s[0:1]
	v_mul_lo_u32 v2, v2, s7
	v_or_b32_e32 v167, v2, v3
	v_lshrrev_b32_e32 v22, 4, v20
	v_and_b32_e32 v24, 6, v20
	v_bfe_u32 v23, v20, 4, 3
	v_bitop3_b32 v25, v22, v20, 7 bitop3:0x28
	v_lshl_or_b32 v170, v25, 4, v165
	v_lshlrev_b32_e32 v21, 7, v21
	v_mov_b32_e32 v168, 0
	v_mov_b32_e32 v148, 0
	v_and_b32_e32 v166, 63, v20
	s_mov_b32 s64, 0
	v_add_u32_e32 v174, 0, v21
	v_add_u32_e32 v178, 0x4000, v26
	s_mov_b32 s41, 0
	v_mov_b32_e32 v149, v148
	v_mov_b32_e32 v150, v148
	v_mov_b32_e32 v151, v148
	v_mov_b32_e32 v144, v148
	v_mov_b32_e32 v145, v148
	v_mov_b32_e32 v146, v148
	v_mov_b32_e32 v147, v148
	v_mov_b32_e32 v140, v148
	v_mov_b32_e32 v141, v148
	v_mov_b32_e32 v142, v148
	v_mov_b32_e32 v143, v148
	v_mov_b32_e32 v136, v148
	v_mov_b32_e32 v137, v148
	v_mov_b32_e32 v138, v148
	v_mov_b32_e32 v139, v148
	v_mov_b32_e32 v48, 0
	v_mov_b32_e32 v49, v168
	v_mov_b32_e32 v50, v168
	v_mov_b32_e32 v51, v168
	v_mov_b32_e32 v52, v168
	v_mov_b32_e32 v53, v168
	v_mov_b32_e32 v54, v168
	v_mov_b32_e32 v55, v168
	v_mov_b32_e32 v56, v168
	v_mov_b32_e32 v57, v168
	v_mov_b32_e32 v58, v168
	v_mov_b32_e32 v59, v168
	v_mov_b32_e32 v60, v168
	v_mov_b32_e32 v61, v168
	v_mov_b32_e32 v62, v168
	v_mov_b32_e32 v63, v168
	s_waitcnt vmcnt(0)
	v_and_b32_e32 v1, 0xffff0000, v112
	v_and_b32_e32 v3, 0xffff0000, v113
	v_lshlrev_b32_e32 v0, 16, v112
	v_lshlrev_b32_e32 v2, 16, v113
	v_and_b32_e32 v5, 0xffff0000, v114
	v_mul_f32_e32 v1, v1, v1
	v_mul_f32_e32 v3, v3, v3
	v_lshlrev_b32_e32 v4, 16, v114
	v_and_b32_e32 v7, 0xffff0000, v115
	v_mul_f32_e32 v5, v5, v5
	v_fmac_f32_e32 v1, v0, v0
	v_fmac_f32_e32 v3, v2, v2
	v_lshlrev_b32_e32 v6, 16, v115
	v_and_b32_e32 v9, 0xffff0000, v116
	v_mul_f32_e32 v7, v7, v7
	v_fmac_f32_e32 v5, v4, v4
	v_add_f32_e32 v0, v1, v3
	v_lshlrev_b32_e32 v8, 16, v116
	v_and_b32_e32 v11, 0xffff0000, v117
	v_mul_f32_e32 v9, v9, v9
	v_fmac_f32_e32 v7, v6, v6
	v_add_f32_e32 v0, v5, v0
	v_lshlrev_b32_e32 v10, 16, v117
	v_and_b32_e32 v13, 0xffff0000, v118
	v_mul_f32_e32 v11, v11, v11
	v_fmac_f32_e32 v9, v8, v8
	v_add_f32_e32 v0, v7, v0
	v_lshlrev_b32_e32 v12, 16, v118
	v_and_b32_e32 v15, 0xffff0000, v119
	v_mul_f32_e32 v13, v13, v13
	v_fmac_f32_e32 v11, v10, v10
	v_add_f32_e32 v0, v9, v0
	v_lshlrev_b32_e32 v14, 16, v119
	v_mul_f32_e32 v15, v15, v15
	v_fmac_f32_e32 v13, v12, v12
	v_add_f32_e32 v0, v11, v0
	v_fmac_f32_e32 v15, v14, v14
	v_add_f32_e32 v0, v13, v0
	v_add_f32_e32 v17, v15, v0
	global_load_dwordx4 v[0:3], v167, s[48:49]
	global_load_dwordx4 v[4:7], v167, s[4:5]
	v_add_u32_e32 v12, 0x2000, v26
	global_load_dwordx4 v[8:11], v12, s[2:3]
	s_nop 0
	global_load_dwordx4 v[12:15], v12, s[62:63]
	v_and_b32_e32 v18, 0xffff0000, v120
	v_lshlrev_b32_e32 v16, 16, v120
	v_mul_f32_e32 v18, v18, v18
	v_fmac_f32_e32 v18, v16, v16
	v_add_f32_e32 v16, v18, v17
	v_and_b32_e32 v18, 0xffff0000, v121
	v_lshlrev_b32_e32 v17, 16, v121
	v_mul_f32_e32 v18, v18, v18
	v_fmac_f32_e32 v18, v17, v17
	v_add_f32_e32 v28, v18, v16
	v_and_b32_e32 v19, 0xffff0000, v123
	v_and_b32_e32 v18, 0xffff0000, v122
	v_lshlrev_b32_e32 v17, 16, v123
	v_lshlrev_b32_e32 v16, 16, v122
	v_pk_mul_f32 v[18:19], v[18:19], v[18:19]
	v_mov_b32_e32 v32, 0
	v_pk_fma_f32 v[16:17], v[16:17], v[16:17], v[18:19]
	v_and_b32_e32 v19, 0xffff0000, v125
	v_add_f32_e32 v16, v16, v28
	v_and_b32_e32 v18, 0xffff0000, v124
	v_add_f32_e32 v28, v17, v16
	v_lshlrev_b32_e32 v17, 16, v125
	v_lshlrev_b32_e32 v16, 16, v124
	v_pk_mul_f32 v[18:19], v[18:19], v[18:19]
	v_mov_b32_e32 v33, v168
	v_pk_fma_f32 v[16:17], v[16:17], v[16:17], v[18:19]
	v_and_b32_e32 v19, 0xffff0000, v127
	v_add_f32_e32 v16, v16, v28
	v_and_b32_e32 v18, 0xffff0000, v126
	v_add_f32_e32 v28, v17, v16
	v_lshlrev_b32_e32 v17, 16, v127
	v_lshlrev_b32_e32 v16, 16, v126
	v_pk_mul_f32 v[18:19], v[18:19], v[18:19]
	v_mov_b32_e32 v34, v168
	v_pk_fma_f32 v[16:17], v[16:17], v[16:17], v[18:19]
	v_and_b32_e32 v18, 64, v229
	v_add_f32_e32 v16, v16, v28
	v_add_f32_e32 v16, v17, v16
	v_xor_b32_e32 v17, 32, v229
	v_add_u32_e32 v18, 64, v18
	v_cmp_lt_i32_e32 vcc, v17, v18
	v_lshlrev_b32_e32 v19, 3, v20
	v_bitop3_b32 v18, v22, v24, 7 bitop3:0x6c
	v_cndmask_b32_e32 v17, v229, v17, vcc
	v_lshlrev_b32_e32 v164, 2, v17
	ds_bpermute_b32 v17, v164, v16
	v_and_b32_e32 v19, 8, v19
	v_bitop3_b32 v22, v24, v23, 1 bitop3:0x36
	v_lshl_or_b32 v172, v18, 4, v19
	v_lshl_or_b32 v169, v22, 4, v19
	s_waitcnt lgkmcnt(0)
	v_add_f32_e32 v16, v16, v17
	v_mul_f32_e32 v16, v27, v16
	v_mul_f32_e32 v17, 0x4f800000, v16
	v_cmp_gt_f32_e32 vcc, s92, v16
	v_mov_b32_e32 v35, v168
	v_mov_b32_e32 v36, v168
	v_cndmask_b32_e32 v16, v16, v17, vcc
	v_sqrt_f32_e32 v17, v16
	v_mov_b32_e32 v37, v168
	v_mov_b32_e32 v38, v168
	v_mov_b32_e32 v39, v168
	v_add_u32_e32 v18, -1, v17
	v_fma_f32 v19, -v18, v17, v16
	v_cmp_ge_f32_e64 s[0:1], 0, v19
	v_add_u32_e32 v19, 1, v17
	v_mov_b32_e32 v40, v168
	v_cndmask_b32_e64 v18, v17, v18, s[0:1]
	v_fma_f32 v17, -v19, v17, v16
	v_cmp_lt_f32_e64 s[0:1], 0, v17
	v_mov_b32_e32 v41, v168
	v_mov_b32_e32 v42, v168
	v_cndmask_b32_e64 v17, v18, v19, s[0:1]
	v_mul_f32_e32 v18, 0x37800000, v17
	v_cndmask_b32_e32 v17, v17, v18, vcc
	v_cmp_class_f32_e32 vcc, v16, v228
	v_add_u32_e32 v18, 0, v165
	v_add_u32_e32 v19, v18, v172
	v_cndmask_b32_e32 v16, v17, v16, vcc
	v_fmamk_f32 v16, v16, 0x3f828f5c, v227
	v_add_u32_e32 v17, 0, v170
	v_xor_b32_e32 v64, 0x80000000, v16
	v_lshrrev_b32_e32 v16, 1, v20
	s_lshl_b32 s0, s59, 13
	ds_write_b128 v17, v[128:131]
	ds_write_b128 v17, v[132:135] offset:8192
	s_waitcnt vmcnt(3)
	ds_write_b64 v19, v[0:1] offset:49152
	v_add_u32_e32 v0, v18, v169
	s_waitcnt vmcnt(2)
	ds_write_b64 v19, v[4:5] offset:57344
	ds_write2st64_b64 v0, v[2:3], v[6:7] offset0:96 offset1:112
	s_waitcnt vmcnt(1)
	ds_write_b128 v17, v[8:11] offset:16384
	s_waitcnt vmcnt(0)
	ds_write_b128 v17, v[12:15] offset:24576
	s_add_i32 s0, s0, 0
	v_bitop3_b32 v0, v163, v16, 7 bitop3:0x78
	v_add_u32_e32 v177, s0, v21
	v_lshlrev_b32_e32 v176, 4, v0
	v_add_u32_e32 v4, v177, v176
	s_waitcnt lgkmcnt(0)
	s_barrier
	ds_read_b128 v[0:3], v4
	ds_read_b128 v[4:7], v4 offset:4096
	v_mov_b32_e32 v65, v64
	v_mov_b32_e32 v66, v64
	v_mov_b32_e32 v67, v64
	v_mov_b32_e32 v68, v64
	v_mov_b32_e32 v69, v64
	v_mov_b32_e32 v70, v64
	v_mov_b32_e32 v71, v64
	v_mov_b32_e32 v72, v64
	v_mov_b32_e32 v73, v64
	v_mov_b32_e32 v74, v64
	v_mov_b32_e32 v75, v64
	v_mov_b32_e32 v76, v64
	v_mov_b32_e32 v77, v64
	v_mov_b32_e32 v78, v64
	v_mov_b32_e32 v79, v64
	v_bfe_u32 v16, v20, 1, 3
	v_mov_b32_e32 v43, v168
	s_waitcnt lgkmcnt(1)
	v_mfma_f32_32x32x16_bf16 v[96:111], v[0:3], v[112:115], v[64:79]
	v_bitop3_b32 v0, v163, v16, 2 bitop3:0x36
	v_lshlrev_b32_e32 v175, 4, v0
	v_add_u32_e32 v8, v177, v175
	ds_read_b128 v[0:3], v8
	ds_read_b128 v[8:11], v8 offset:4096
	v_mov_b32_e32 v44, v168
	v_mov_b32_e32 v45, v168
	v_mov_b32_e32 v46, v168
	s_waitcnt lgkmcnt(2)
	v_mfma_f32_32x32x16_bf16 v[80:95], v[4:7], v[112:115], v[64:79]
	v_mov_b32_e32 v47, v168
	v_mov_b32_e32 v20, v168
	v_mov_b32_e32 v21, v168
	v_mov_b32_e32 v22, v168
	v_mov_b32_e32 v23, v168
	v_mov_b32_e32 v24, v168
	v_mov_b32_e32 v25, v168
	s_waitcnt lgkmcnt(1)
	v_mfma_f32_32x32x16_bf16 v[96:111], v[0:3], v[116:119], v[96:111]
	v_bitop3_b32 v0, v163, v16, 4 bitop3:0x36
	v_lshlrev_b32_e32 v173, 4, v0
	v_add_u32_e32 v12, v177, v173
	ds_read_b128 v[0:3], v12
	ds_read_b128 v[12:15], v12 offset:4096
	v_mov_b32_e32 v26, v168
	v_mov_b32_e32 v27, v168
	v_mov_b32_e32 v28, v168
	s_waitcnt lgkmcnt(2)
	v_mfma_f32_32x32x16_bf16 v[80:95], v[8:11], v[116:119], v[80:95]
	v_mov_b32_e32 v29, v168
	v_mov_b32_e32 v30, v168
	v_mov_b32_e32 v31, v168
	v_mov_b32_e32 v4, v168
	v_mov_b32_e32 v5, v168
	v_mov_b32_e32 v6, v168
	v_mov_b32_e32 v7, v168
	s_waitcnt lgkmcnt(1)
	v_mfma_f32_32x32x16_bf16 v[96:111], v[0:3], v[120:123], v[96:111]
	v_bitop3_b32 v0, v163, v16, 6 bitop3:0x36
	v_lshlrev_b32_e32 v171, 4, v0
	v_add_u32_e32 v16, v177, v171
	ds_read_b128 v[0:3], v16
	ds_read_b128 v[16:19], v16 offset:4096
	v_mov_b32_e32 v8, v168
	v_mov_b32_e32 v9, v168
	v_mov_b32_e32 v10, v168
	s_waitcnt lgkmcnt(2)
	v_mfma_f32_32x32x16_bf16 v[80:95], v[12:15], v[120:123], v[80:95]
	v_mov_b32_e32 v11, v168
	v_mov_b32_e32 v12, v168
	v_mov_b32_e32 v13, v168
	v_mov_b32_e32 v14, v168
	v_mov_b32_e32 v15, v168
	s_waitcnt lgkmcnt(1)
	v_mfma_f32_32x32x16_bf16 v[96:111], v[0:3], v[124:127], v[96:111]
	v_mov_b32_e32 v0, 0
	v_mov_b32_e32 v1, v168
	v_mov_b32_e32 v2, v168
	v_mov_b32_e32 v3, v168
	s_waitcnt lgkmcnt(0)
	v_mfma_f32_32x32x16_bf16 v[80:95], v[16:19], v[124:127], v[80:95]
	v_mov_b32_e32 v16, 0
	v_mov_b32_e32 v17, v168
	v_mov_b32_e32 v18, v168
	v_mov_b32_e32 v19, v168
